# P10 ordered-float key mapping with v_bitop3 (one VALU op fewer per key)
# speedup vs baseline: 1.0030x; 1.0030x over previous
; #define MFMA(a, b, c) __builtin_amdgcn_mfma_f32_16x16x32_bf16((a), (b), (c), 0, 0, 0)
; DI unsigned ordf(float f) { unsigned u = __float_as_uint(f); return (u & 0x80000000u) ? ~u : (u | 0x80000000u); }
; DI void peer_topk_wave(const Params& p, int item, unsigned* lds  ) {
;   const int lane = threadIdx.x & 63, r = lane & 15, kg = lane >> 4;
;   const int h = item & 7, row0 = (item >> 3) * 16;
;   unsigned win[2][16];
; #pragma unroll
;   for (int pp = 0; pp < 2; ++pp) {
;     bf16x8 qf[4];
; #pragma unroll
;     for (int ks = 0; ks < 4; ++ks) qf[ks] = *(const bf16x8*)&p.pq[(size_t)(row0 + r) * 2048 + h * 256 + pp * 128 + ks * 32 + kg * 8];
;     unsigned kk[32];
;     const u16* sk = p.subkb + (size_t)(h * 2 + pp) * 16384;
; #pragma unroll
;     for (int mt = 0; mt < 8; ++mt) {
;       f32x4 a = (f32x4){0.f, 0.f, 0.f, 0.f};
; #pragma unroll
;       for (int ks = 0; ks < 4; ++ks) {
;         bf16x8 kf = *(const bf16x8*)&sk[(mt * 16 + r) * 128 + ks * 32 + kg * 8];
;         a = MFMA(kf, qf[ks], a);
;       }
; #pragma unroll
;       for (int j = 0; j < 4; ++j) kk[mt * 4 + j] = (ordf(a[j]) & ~127u) | (unsigned)(mt * 16 + kg * 4 + j);
.LBB0_1087:
	s_or_b64 exec, exec, s[2:3]
	s_movk_i32 s0, 0x4040
	v_cmp_gt_i32_e32 vcc, s0, v163
	s_waitcnt lgkmcnt(0)
	s_barrier
	s_and_saveexec_b64 s[72:73], vcc
	s_cbranch_execz .LBB0_1304
	v_mov_b32_e32 v3, 0x61
	v_cmp_eq_u32_e64 s[10:11], 2, v175
	v_mov_b32_e32 v5, 0x42
	v_lshlrev_b32_e32 v1, 7, v134
	v_cndmask_b32_e64 v97, v3, 32, s[10:11]
	v_mov_b32_e32 v3, 0x70
	v_cndmask_b32_e64 v98, v3, 33, s[10:11]
	v_mov_b32_e32 v3, 0x71
	v_cndmask_b32_e64 v99, v3, 34, s[10:11]
	v_mov_b32_e32 v3, 0x80
	v_cndmask_b32_e64 v100, v3, 35, s[10:11]
	v_mov_b32_e32 v3, 0x90
	v_cndmask_b32_e64 v101, v3, 36, s[10:11]
	v_mov_b32_e32 v3, 0xa0
	v_cndmask_b32_e64 v102, v3, 48, s[10:11]
	v_mov_b32_e32 v3, 0xb0
	v_cndmask_b32_e64 v103, v3, 49, s[10:11]
	v_mov_b32_e32 v3, 0xc0
	v_cndmask_b32_e64 v104, v3, 50, s[10:11]
	v_mov_b32_e32 v3, 0xd0
	v_cndmask_b32_e64 v105, v3, 51, s[10:11]
	v_mov_b32_e32 v3, 0xe0
	v_cndmask_b32_e64 v106, v3, v5, s[10:11]
	v_mov_b32_e32 v3, 0xf0
	v_mov_b32_e32 v5, 0x50
	v_cndmask_b32_e64 v107, v3, v5, s[10:11]
	v_mov_b32_e32 v3, 0x51
	v_cndmask_b32_e64 v108, 0, v3, s[10:11]
	v_mov_b32_e32 v3, 0x60
	v_cndmask_b32_e64 v109, 0, v3, s[10:11]
	v_lshlrev_b32_e32 v3, 11, v174
	v_add_u32_e32 v110, v3, v1
	v_and_b32_e32 v3, 64, v128
	v_or_b32_e32 v0, v171, v1
	v_xor_b32_e32 v1, 16, v128
	v_add_u32_e32 v3, 64, v3
	v_cmp_lt_i32_e32 vcc, v1, v3
	v_mov_b32_e32 v17, 0
	v_or_b32_e32 v2, 32, v0
	v_cndmask_b32_e32 v1, v128, v1, vcc
	v_lshlrev_b32_e32 v111, 2, v1
	v_xor_b32_e32 v1, 32, v128
	v_cmp_lt_i32_e32 vcc, v1, v3
	v_or_b32_e32 v4, 64, v0
	v_or_b32_e32 v6, 0x60, v0
	v_cndmask_b32_e32 v1, v128, v1, vcc
	v_or_b32_e32 v8, 0x800, v0
	v_or_b32_e32 v10, 0x820, v0
	v_or_b32_e32 v12, 0x840, v0
	v_or_b32_e32 v14, 0x860, v0
	v_or_b32_e32 v16, 0x1000, v0
	v_or_b32_e32 v32, 0x1020, v0
	v_or_b32_e32 v34, 0x1040, v0
	v_or_b32_e32 v36, 0x1060, v0
	v_or_b32_e32 v38, 0x1800, v0
	v_or_b32_e32 v40, 0x1820, v0
	v_or_b32_e32 v42, 0x1840, v0
	v_or_b32_e32 v44, 0x1860, v0
	v_or_b32_e32 v46, 0x2000, v0
	v_or_b32_e32 v48, 0x2020, v0
	v_or_b32_e32 v50, 0x2040, v0
	v_or_b32_e32 v52, 0x2060, v0
	v_or_b32_e32 v54, 0x2800, v0
	v_or_b32_e32 v56, 0x2820, v0
	v_or_b32_e32 v58, 0x2840, v0
	v_or_b32_e32 v60, 0x2860, v0
	v_or_b32_e32 v62, 0x3000, v0
	v_or_b32_e32 v64, 0x3020, v0
	v_or_b32_e32 v66, 0x3040, v0
	v_or_b32_e32 v68, 0x3060, v0
	v_or_b32_e32 v70, 0x3800, v0
	v_or_b32_e32 v72, 0x3820, v0
	v_or_b32_e32 v74, 0x3840, v0
	v_or_b32_e32 v76, 0x3860, v0
	v_lshlrev_b32_e32 v112, 2, v1
	v_lshlrev_b32_e32 v1, 1, v174
	v_or_b32_e32 v90, 16, v170
	v_or_b32_e32 v91, 32, v170
	v_or_b32_e32 v92, 48, v170
	v_or_b32_e32 v93, 64, v170
	v_or_b32_e32 v94, 0x50, v170
	v_or_b32_e32 v95, 0x60, v170
	v_or_b32_e32 v96, 0x70, v170
	v_cmp_gt_u32_e64 s[4:5], 2, v175
	v_cmp_eq_u32_e64 s[12:13], 3, v175
	v_or_b32_e32 v113, 1, v170
	v_or_b32_e32 v114, 2, v170
	v_or_b32_e32 v115, 3, v170
	v_or_b32_e32 v116, 17, v170
	v_or_b32_e32 v117, 18, v170
	v_or_b32_e32 v118, 19, v170
	v_or_b32_e32 v119, 33, v170
	v_or_b32_e32 v120, 34, v170
	v_or_b32_e32 v121, 35, v170
	v_or_b32_e32 v122, 49, v170
	v_or_b32_e32 v123, 50, v170
	v_or_b32_e32 v124, 51, v170
	v_or_b32_e32 v125, 0x41, v170
	v_or_b32_e32 v126, 0x42, v170
	v_or_b32_e32 v127, 0x43, v170
	v_or_b32_e32 v129, 0x51, v170
	v_or_b32_e32 v130, 0x52, v170
	v_or_b32_e32 v131, 0x53, v170
	v_or_b32_e32 v135, 0x61, v170
	v_or_b32_e32 v136, 0x62, v170
	v_or_b32_e32 v137, 0x63, v170
	v_or_b32_e32 v138, 0x71, v170
	v_or_b32_e32 v139, 0x72, v170
	v_or_b32_e32 v140, 0x73, v170
	s_lshr_b32 s89, s86, 3
	s_lshl_b32 s89, s89, 2
	v_add_u32_e32 v141, s89, v174
	v_lshlrev_b32_e32 v141, 3, v141
	s_and_b32 s89, s86, 7
	v_or_b32_e32 v141, s89, v141
	v_mov_b32_e32 v238, v141
	v_lshlrev_b32_e32 v141, 1, v141
	s_lshl_b32 s79, s84, 3
	s_mov_b64 s[74:75], 0
	s_mov_b32 s88, 0
	s_mov_b64 s[90:91], 0x1000000
	v_mov_b32_e32 v142, 0x10178
	v_lshlrev_b32_e32 v18, 1, v171
	v_mov_b32_e32 v19, v17
	v_mov_b32_e32 v143, 0x10110
	v_lshlrev_b32_e32 v20, 1, v0
	v_mov_b32_e32 v21, v17
	s_movk_i32 s80, 0xff80
	v_lshlrev_b32_e32 v22, 1, v8
	v_mov_b32_e32 v23, v17
	v_lshlrev_b32_e32 v24, 1, v10
	v_mov_b32_e32 v25, v17
	v_lshlrev_b32_e32 v26, 1, v12
	v_mov_b32_e32 v27, v17
	v_lshlrev_b32_e32 v28, 1, v14
	v_mov_b32_e32 v29, v17
	v_lshlrev_b32_e32 v30, 1, v16
	v_mov_b32_e32 v31, v17
	v_lshlrev_b32_e32 v32, 1, v32
	v_mov_b32_e32 v33, v17
	v_lshlrev_b32_e32 v34, 1, v34
	v_mov_b32_e32 v35, v17
	v_lshlrev_b32_e32 v36, 1, v36
	v_mov_b32_e32 v37, v17
	v_lshlrev_b32_e32 v38, 1, v38
	v_mov_b32_e32 v39, v17
	v_lshlrev_b32_e32 v40, 1, v40
	v_mov_b32_e32 v41, v17
	v_lshlrev_b32_e32 v42, 1, v42
	v_mov_b32_e32 v43, v17
	v_lshlrev_b32_e32 v44, 1, v44
	v_mov_b32_e32 v45, v17
	v_lshlrev_b32_e32 v46, 1, v46
	v_mov_b32_e32 v47, v17
	v_lshlrev_b32_e32 v48, 1, v48
	v_mov_b32_e32 v49, v17
	v_lshlrev_b32_e32 v50, 1, v50
	v_mov_b32_e32 v51, v17
	v_lshlrev_b32_e32 v52, 1, v52
	v_mov_b32_e32 v53, v17
	v_lshlrev_b32_e32 v54, 1, v54
	v_mov_b32_e32 v55, v17
	v_lshlrev_b32_e32 v56, 1, v56
	v_mov_b32_e32 v57, v17
	v_lshlrev_b32_e32 v58, 1, v58
	v_mov_b32_e32 v59, v17
	v_lshlrev_b32_e32 v60, 1, v60
	v_mov_b32_e32 v61, v17
	v_lshlrev_b32_e32 v62, 1, v62
	v_mov_b32_e32 v63, v17
	v_lshlrev_b32_e32 v64, 1, v64
	v_mov_b32_e32 v65, v17
	v_lshlrev_b32_e32 v66, 1, v66
	v_mov_b32_e32 v67, v17
	v_lshlrev_b32_e32 v68, 1, v68
	v_mov_b32_e32 v69, v17
	v_lshlrev_b32_e32 v70, 1, v70
	v_mov_b32_e32 v71, v17
	v_lshlrev_b32_e32 v72, 1, v72
	v_mov_b32_e32 v73, v17
	v_lshlrev_b32_e32 v74, 1, v74
	v_mov_b32_e32 v75, v17
	v_lshlrev_b32_e32 v76, 1, v76
	v_mov_b32_e32 v77, v17
	s_mov_b64 s[76:77], 0x8000
	v_lshlrev_b32_e32 v78, 1, v2
	v_mov_b32_e32 v79, v17
	v_lshlrev_b32_e32 v80, 1, v4
	v_mov_b32_e32 v81, v17
	v_lshlrev_b32_e32 v82, 1, v6
	v_mov_b32_e32 v83, v17
	s_movk_i32 s81, 0x7f
	s_movk_i32 s82, 0xff00
	s_movk_i32 s83, 0xff
	v_mov_b32_e32 v144, 0x101b0
	s_movk_i32 s86, 0x403f
	v_mov_b32_e32 v145, v238
	v_lshl_add_u32 v239, v174, 6, v128
	v_lshrrev_b32_e32 v240, 4, v239
	v_lshlrev_b32_e32 v239, 4, v239
	v_lshl_add_u32 v240, v240, 4, v239
	v_add_u32_e32 v240, 0x2000, v240
	v_and_b32_e32 v241, 15, v128
	v_mul_u32_u24_e32 v241, 0x110, v241
	v_lshrrev_b32_e32 v242, 4, v128
	v_lshl_add_u32 v241, v242, 4, v241
	v_add_u32_e32 v241, 0x2000, v241
	v_mov_b32_e32 v242, 0x10110
	ds_read_b64 v[242:243], v242
	s_lshl_b32 s92, s89, 16
	s_waitcnt lgkmcnt(0)
; #define MFMA(a, b, c) __builtin_amdgcn_mfma_f32_16x16x32_bf16((a), (b), (c), 0, 0, 0)
; DI void peer_topk_wave(const Params& p, int item, unsigned* lds  ) {
;     ...
;     const u16* sk = p.subkb + (size_t)(h * 2 + pp) * 16384;
; #pragma unroll
;     for (int mt = 0; mt < 8; ++mt) {
;       f32x4 a = (f32x4){0.f, 0.f, 0.f, 0.f};
; #pragma unroll
;       for (int ks = 0; ks < 4; ++ks) {
;         bf16x8 kf = *(const bf16x8*)&sk[(mt * 16 + r) * 128 + ks * 32 + kg * 8];
;         a = MFMA(kf, qf[ks], a);
	v_readfirstlane_b32 s96, v242
	v_readfirstlane_b32 s97, v243
	s_nop 3
	s_add_u32 s96, s96, s92
	s_addc_u32 s97, s97, 0
	s_add_u32 s92, s96, 0x0
	s_addc_u32 s93, s97, 0
	global_load_dwordx4 v[24:27], v239, s[92:93]
	s_add_u32 s92, s96, 0x1000
	s_addc_u32 s93, s97, 0
	global_load_dwordx4 v[28:31], v239, s[92:93]
	s_add_u32 s92, s96, 0x2000
	s_addc_u32 s93, s97, 0
	global_load_dwordx4 v[32:35], v239, s[92:93]
	s_add_u32 s92, s96, 0x3000
	s_addc_u32 s93, s97, 0
	global_load_dwordx4 v[36:39], v239, s[92:93]
	s_add_u32 s92, s96, 0x4000
	s_addc_u32 s93, s97, 0
	global_load_dwordx4 v[40:43], v239, s[92:93]
	s_add_u32 s92, s96, 0x5000
	s_addc_u32 s93, s97, 0
	global_load_dwordx4 v[44:47], v239, s[92:93]
	s_add_u32 s92, s96, 0x6000
	s_addc_u32 s93, s97, 0
	global_load_dwordx4 v[48:51], v239, s[92:93]
	s_add_u32 s92, s96, 0x7000
	s_addc_u32 s93, s97, 0
	global_load_dwordx4 v[52:55], v239, s[92:93]
	s_add_u32 s92, s96, 0x8000
	s_addc_u32 s93, s97, 0
	global_load_dwordx4 v[56:59], v239, s[92:93]
	s_add_u32 s92, s96, 0x9000
	s_addc_u32 s93, s97, 0
	global_load_dwordx4 v[60:63], v239, s[92:93]
	s_add_u32 s92, s96, 0xa000
	s_addc_u32 s93, s97, 0
	global_load_dwordx4 v[64:67], v239, s[92:93]
	s_add_u32 s92, s96, 0xb000
	s_addc_u32 s93, s97, 0
	global_load_dwordx4 v[68:71], v239, s[92:93]
	s_add_u32 s92, s96, 0xc000
	s_addc_u32 s93, s97, 0
	global_load_dwordx4 v[72:75], v239, s[92:93]
	s_waitcnt vmcnt(0)
	ds_write_b128 v240, v[24:27] offset:0
	ds_write_b128 v240, v[28:31] offset:4352
	ds_write_b128 v240, v[32:35] offset:8704
	ds_write_b128 v240, v[36:39] offset:13056
	ds_write_b128 v240, v[40:43] offset:17408
	ds_write_b128 v240, v[44:47] offset:21760
	ds_write_b128 v240, v[48:51] offset:26112
	ds_write_b128 v240, v[52:55] offset:30464
	ds_write_b128 v240, v[56:59] offset:34816
	ds_write_b128 v240, v[60:63] offset:39168
	ds_write_b128 v240, v[64:67] offset:43520
	ds_write_b128 v240, v[68:71] offset:47872
	ds_write_b128 v240, v[72:75] offset:52224
	s_waitcnt lgkmcnt(0)
	s_barrier
	s_mov_b32 s93, 0x80000000
	s_branch .LBB0_1091

; #define MFMA(a, b, c) __builtin_amdgcn_mfma_f32_16x16x32_bf16((a), (b), (c), 0, 0, 0)
; DI unsigned ordf(float f) { unsigned u = __float_as_uint(f); return (u & 0x80000000u) ? ~u : (u | 0x80000000u); }
; DI void peer_topk_wave(const Params& p, int item, unsigned* lds  ) {
;     ...
; #pragma unroll
;     for (int mt = 0; mt < 8; ++mt) {
;       f32x4 a = (f32x4){0.f, 0.f, 0.f, 0.f};
; #pragma unroll
;       for (int ks = 0; ks < 4; ++ks) {
;         bf16x8 kf = *(const bf16x8*)&sk[(mt * 16 + r) * 128 + ks * 32 + kg * 8];
;         a = MFMA(kf, qf[ks], a);
;       }
; #pragma unroll
;       for (int j = 0; j < 4; ++j) kk[mt * 4 + j] = (ordf(a[j]) & ~127u) | (unsigned)(mt * 16 + kg * 4 + j);
.Lp10q_done0:
	v_readfirstlane_b32 s0, v86
	v_readfirstlane_b32 s1, v87
	s_nop 3
	s_add_u32 s2, s0, 0x0
	s_addc_u32 s3, s1, 0
	ds_read_b128 v[24:27], v241 offset:0
	ds_read_b128 v[28:31], v241 offset:64
	ds_read_b128 v[32:35], v241 offset:128
	ds_read_b128 v[36:39], v241 offset:192
	s_add_u32 s2, s0, 0x1000
	s_addc_u32 s3, s1, 0
	ds_read_b128 v[40:43], v241 offset:4352
	ds_read_b128 v[44:47], v241 offset:4416
	ds_read_b128 v[48:51], v241 offset:4480
	ds_read_b128 v[52:55], v241 offset:4544
	s_add_u32 s2, s0, 0x2000
	s_addc_u32 s3, s1, 0
	ds_read_b128 v[56:59], v241 offset:8704
	ds_read_b128 v[60:63], v241 offset:8768
	ds_read_b128 v[64:67], v241 offset:8832
	ds_read_b128 v[68:71], v241 offset:8896
	s_add_u32 s2, s0, 0x3000
	s_addc_u32 s3, s1, 0
	ds_read_b128 v[72:75], v241 offset:13056
	ds_read_b128 v[76:79], v241 offset:13120
	ds_read_b128 v[80:83], v241 offset:13184
	s_waitcnt vmcnt(0) lgkmcnt(11)
	v_mfma_f32_16x16x32_bf16 v[190:193], v[24:27], v[12:15], 0
	v_mfma_f32_16x16x32_bf16 v[190:193], v[28:31], v[8:11], v[190:193]
	v_mfma_f32_16x16x32_bf16 v[190:193], v[32:35], v[4:7], v[190:193]
	v_mfma_f32_16x16x32_bf16 v[190:193], v[36:39], v[0:3], v[190:193]
	ds_read_b128 v[24:27], v241 offset:13248
	s_add_u32 s2, s0, 0x4000
	s_addc_u32 s3, s1, 0
	ds_read_b128 v[28:31], v241 offset:17408
	ds_read_b128 v[32:35], v241 offset:17472
	ds_read_b128 v[36:39], v241 offset:17536
	s_waitcnt lgkmcnt(11)
	v_mfma_f32_16x16x32_bf16 v[198:201], v[40:43], v[12:15], 0
	v_mfma_f32_16x16x32_bf16 v[198:201], v[44:47], v[8:11], v[198:201]
	v_mfma_f32_16x16x32_bf16 v[198:201], v[48:51], v[4:7], v[198:201]
	v_mfma_f32_16x16x32_bf16 v[198:201], v[52:55], v[0:3], v[198:201]
	ds_read_b128 v[40:43], v241 offset:17600
	s_add_u32 s2, s0, 0x5000
	s_addc_u32 s3, s1, 0
	ds_read_b128 v[44:47], v241 offset:21760
	ds_read_b128 v[48:51], v241 offset:21824
	ds_read_b128 v[52:55], v241 offset:21888
	s_nop 7
	s_nop 3
	v_ashrrev_i32_e32 v197, 31, v190
	v_bitop3_b32 v197, v190, v197, s93 bitop3:0x1e
	v_and_or_b32 v147, v197, s80, v170
	v_ashrrev_i32_e32 v202, 31, v191
	v_bitop3_b32 v202, v191, v202, s93 bitop3:0x1e
	v_and_or_b32 v148, v202, s80, v113
	v_ashrrev_i32_e32 v197, 31, v192
	v_bitop3_b32 v197, v192, v197, s93 bitop3:0x1e
	v_and_or_b32 v149, v197, s80, v114
	v_ashrrev_i32_e32 v202, 31, v193
	v_bitop3_b32 v202, v193, v202, s93 bitop3:0x1e
	v_and_or_b32 v150, v202, s80, v115
	s_waitcnt lgkmcnt(11)
	v_mfma_f32_16x16x32_bf16 v[190:193], v[56:59], v[12:15], 0
	v_mfma_f32_16x16x32_bf16 v[190:193], v[60:63], v[8:11], v[190:193]
	v_mfma_f32_16x16x32_bf16 v[190:193], v[64:67], v[4:7], v[190:193]
	v_mfma_f32_16x16x32_bf16 v[190:193], v[68:71], v[0:3], v[190:193]
	ds_read_b128 v[56:59], v241 offset:21952
	s_add_u32 s2, s0, 0x6000
	s_addc_u32 s3, s1, 0
	ds_read_b128 v[60:63], v241 offset:26112
	ds_read_b128 v[64:67], v241 offset:26176
	ds_read_b128 v[68:71], v241 offset:26240
	s_nop 7
	s_nop 3
	v_ashrrev_i32_e32 v197, 31, v198
	v_bitop3_b32 v197, v198, v197, s93 bitop3:0x1e
	v_and_or_b32 v151, v197, s80, v90
	v_ashrrev_i32_e32 v202, 31, v199
	v_bitop3_b32 v202, v199, v202, s93 bitop3:0x1e
	v_and_or_b32 v152, v202, s80, v116
	v_ashrrev_i32_e32 v197, 31, v200
	v_bitop3_b32 v197, v200, v197, s93 bitop3:0x1e
	v_and_or_b32 v153, v197, s80, v117
	v_ashrrev_i32_e32 v202, 31, v201
	v_bitop3_b32 v202, v201, v202, s93 bitop3:0x1e
	v_and_or_b32 v154, v202, s80, v118
	s_waitcnt lgkmcnt(11)
	v_mfma_f32_16x16x32_bf16 v[198:201], v[72:75], v[12:15], 0
	v_mfma_f32_16x16x32_bf16 v[198:201], v[76:79], v[8:11], v[198:201]
	v_mfma_f32_16x16x32_bf16 v[198:201], v[80:83], v[4:7], v[198:201]
	v_mfma_f32_16x16x32_bf16 v[198:201], v[24:27], v[0:3], v[198:201]
	ds_read_b128 v[72:75], v241 offset:26304
	s_add_u32 s2, s0, 0x7000
	s_addc_u32 s3, s1, 0
	ds_read_b128 v[76:79], v241 offset:30464
	ds_read_b128 v[80:83], v241 offset:30528
	ds_read_b128 v[24:27], v241 offset:30592
	s_nop 7
	s_nop 3
	v_ashrrev_i32_e32 v197, 31, v190
	v_bitop3_b32 v197, v190, v197, s93 bitop3:0x1e
	v_and_or_b32 v155, v197, s80, v91
	v_ashrrev_i32_e32 v202, 31, v191
	v_bitop3_b32 v202, v191, v202, s93 bitop3:0x1e
	v_and_or_b32 v156, v202, s80, v119
	v_ashrrev_i32_e32 v197, 31, v192
	v_bitop3_b32 v197, v192, v197, s93 bitop3:0x1e
	v_and_or_b32 v157, v197, s80, v120
	v_ashrrev_i32_e32 v202, 31, v193
	v_bitop3_b32 v202, v193, v202, s93 bitop3:0x1e
	v_and_or_b32 v158, v202, s80, v121
	s_waitcnt lgkmcnt(11)
	v_mfma_f32_16x16x32_bf16 v[190:193], v[28:31], v[12:15], 0
	v_mfma_f32_16x16x32_bf16 v[190:193], v[32:35], v[8:11], v[190:193]
	v_mfma_f32_16x16x32_bf16 v[190:193], v[36:39], v[4:7], v[190:193]
	v_mfma_f32_16x16x32_bf16 v[190:193], v[40:43], v[0:3], v[190:193]
	ds_read_b128 v[28:31], v241 offset:30656
	s_nop 7
	s_nop 3
	v_ashrrev_i32_e32 v197, 31, v198
	v_bitop3_b32 v197, v198, v197, s93 bitop3:0x1e
	v_and_or_b32 v159, v197, s80, v92
	v_ashrrev_i32_e32 v202, 31, v199
	v_bitop3_b32 v202, v199, v202, s93 bitop3:0x1e
	v_and_or_b32 v160, v202, s80, v122
	v_ashrrev_i32_e32 v197, 31, v200
	v_bitop3_b32 v197, v200, v197, s93 bitop3:0x1e
	v_and_or_b32 v161, v197, s80, v123
	v_ashrrev_i32_e32 v202, 31, v201
	v_bitop3_b32 v202, v201, v202, s93 bitop3:0x1e
	v_and_or_b32 v162, v202, s80, v124
	s_waitcnt lgkmcnt(8)
	v_mfma_f32_16x16x32_bf16 v[198:201], v[44:47], v[12:15], 0
	v_mfma_f32_16x16x32_bf16 v[198:201], v[48:51], v[8:11], v[198:201]
	v_mfma_f32_16x16x32_bf16 v[198:201], v[52:55], v[4:7], v[198:201]
	v_mfma_f32_16x16x32_bf16 v[198:201], v[56:59], v[0:3], v[198:201]
	s_nop 7
	s_nop 3
	v_ashrrev_i32_e32 v197, 31, v190
	v_bitop3_b32 v197, v190, v197, s93 bitop3:0x1e
	v_and_or_b32 v164, v197, s80, v93
	v_ashrrev_i32_e32 v202, 31, v191
	v_bitop3_b32 v202, v191, v202, s93 bitop3:0x1e
	v_and_or_b32 v165, v202, s80, v125
	v_ashrrev_i32_e32 v197, 31, v192
	v_bitop3_b32 v197, v192, v197, s93 bitop3:0x1e
	v_and_or_b32 v166, v197, s80, v126
	v_ashrrev_i32_e32 v202, 31, v193
	v_bitop3_b32 v202, v193, v202, s93 bitop3:0x1e
	v_and_or_b32 v167, v202, s80, v127
	s_waitcnt lgkmcnt(4)
; DI unsigned ordf(float f) { unsigned u = __float_as_uint(f); return (u & 0x80000000u) ? ~u : (u | 0x80000000u); }
; DI void peer_topk_wave(const Params& p, int item, unsigned* lds  ) {
;     ...
; #pragma unroll
;       for (int j = 0; j < 4; ++j) kk[mt * 4 + j] = (ordf(a[j]) & ~127u) | (unsigned)(mt * 16 + kg * 4 + j);
;     }
; #pragma unroll
;     for (int rr = 0; rr < 16; ++rr) {
;       unsigned m = 0;
; #pragma unroll
;       for (int i = 0; i < 32; ++i) m = umax(m, kk[i]);
;       m = umax(m, (unsigned)__shfl_xor((int)m, 16));
;       m = umax(m, (unsigned)__shfl_xor((int)m, 32));
;       win[pp][rr] = m;
	v_mfma_f32_16x16x32_bf16 v[190:193], v[60:63], v[12:15], 0
	v_mfma_f32_16x16x32_bf16 v[190:193], v[64:67], v[8:11], v[190:193]
	v_mfma_f32_16x16x32_bf16 v[190:193], v[68:71], v[4:7], v[190:193]
	v_mfma_f32_16x16x32_bf16 v[190:193], v[72:75], v[0:3], v[190:193]
	s_nop 7
	s_nop 3
	v_ashrrev_i32_e32 v197, 31, v198
	v_bitop3_b32 v197, v198, v197, s93 bitop3:0x1e
	v_and_or_b32 v168, v197, s80, v94
	v_ashrrev_i32_e32 v202, 31, v199
	v_bitop3_b32 v202, v199, v202, s93 bitop3:0x1e
	v_and_or_b32 v169, v202, s80, v129
	v_ashrrev_i32_e32 v197, 31, v200
	v_bitop3_b32 v197, v200, v197, s93 bitop3:0x1e
	v_and_or_b32 v171, v197, s80, v130
	v_ashrrev_i32_e32 v202, 31, v201
	v_bitop3_b32 v202, v201, v202, s93 bitop3:0x1e
	v_and_or_b32 v172, v202, s80, v131
	s_waitcnt lgkmcnt(0)
	v_mfma_f32_16x16x32_bf16 v[198:201], v[76:79], v[12:15], 0
	v_mfma_f32_16x16x32_bf16 v[198:201], v[80:83], v[8:11], v[198:201]
	v_mfma_f32_16x16x32_bf16 v[198:201], v[24:27], v[4:7], v[198:201]
	v_mfma_f32_16x16x32_bf16 v[198:201], v[28:31], v[0:3], v[198:201]
	s_nop 7
	s_nop 3
	v_ashrrev_i32_e32 v197, 31, v190
	v_bitop3_b32 v197, v190, v197, s93 bitop3:0x1e
	v_and_or_b32 v173, v197, s80, v95
	v_ashrrev_i32_e32 v202, 31, v191
	v_bitop3_b32 v202, v191, v202, s93 bitop3:0x1e
	v_and_or_b32 v180, v202, s80, v135
	v_ashrrev_i32_e32 v197, 31, v192
	v_bitop3_b32 v197, v192, v197, s93 bitop3:0x1e
	v_and_or_b32 v181, v197, s80, v136
	v_ashrrev_i32_e32 v202, 31, v193
	v_bitop3_b32 v202, v193, v202, s93 bitop3:0x1e
	v_and_or_b32 v182, v202, s80, v137
	s_nop 7
	s_nop 3
	v_ashrrev_i32_e32 v197, 31, v198
	v_bitop3_b32 v197, v198, v197, s93 bitop3:0x1e
	v_and_or_b32 v0, v197, s80, v96
	v_ashrrev_i32_e32 v202, 31, v199
	v_bitop3_b32 v202, v199, v202, s93 bitop3:0x1e
	v_and_or_b32 v1, v202, s80, v138
	v_ashrrev_i32_e32 v197, 31, v200
	v_bitop3_b32 v197, v200, v197, s93 bitop3:0x1e
	v_and_or_b32 v2, v197, s80, v139
	v_ashrrev_i32_e32 v202, 31, v201
	v_bitop3_b32 v202, v201, v202, s93 bitop3:0x1e
	v_and_or_b32 v3, v202, s80, v140
	v_max_u32_e32 v24, v147, v148
	v_max3_u32 v24, v24, v149, v150
	v_max3_u32 v24, v24, v151, v152
	v_max3_u32 v24, v24, v153, v154
	v_max3_u32 v24, v24, v155, v156
	v_max3_u32 v24, v24, v157, v158
	v_max3_u32 v24, v24, v159, v160
	v_max3_u32 v24, v24, v161, v162
	v_max3_u32 v24, v24, v164, v165
	v_max3_u32 v24, v24, v166, v167
	v_max3_u32 v24, v24, v168, v169
	v_max3_u32 v24, v24, v171, v172
	v_max3_u32 v24, v24, v173, v180
	v_max3_u32 v24, v24, v181, v182
	v_max3_u32 v24, v24, v0, v1
	v_max3_u32 v24, v24, v2, v3
	v_mov_b32_e32 v25, v24
	s_nop 1
	v_permlane16_swap_b32 v24, v25
	s_nop 1
	v_max_u32_e32 v24, v24, v25
	v_mov_b32_e32 v25, v24
	s_nop 1
	v_permlane32_swap_b32 v24, v25
	s_nop 1
	v_max_u32_e32 v40, v24, v25
	v_sub_u32_e32 v26, v147, v40
	v_sub_u32_e32 v27, v148, v40
	v_max_u32_e32 v24, v26, v27
	v_sub_u32_e32 v28, v149, v40
	v_sub_u32_e32 v29, v150, v40
	v_max3_u32 v24, v24, v28, v29
	v_sub_u32_e32 v30, v151, v40
	v_sub_u32_e32 v31, v152, v40
	v_max3_u32 v24, v24, v30, v31
	v_sub_u32_e32 v32, v153, v40
	v_sub_u32_e32 v33, v154, v40
	v_max3_u32 v24, v24, v32, v33
	v_sub_u32_e32 v26, v155, v40
	v_sub_u32_e32 v27, v156, v40
	v_max3_u32 v24, v24, v26, v27
	v_sub_u32_e32 v28, v157, v40
	v_sub_u32_e32 v29, v158, v40
	v_max3_u32 v24, v24, v28, v29
	v_sub_u32_e32 v30, v159, v40
	v_sub_u32_e32 v31, v160, v40
	v_max3_u32 v24, v24, v30, v31
	v_sub_u32_e32 v32, v161, v40
	v_sub_u32_e32 v33, v162, v40
	v_max3_u32 v24, v24, v32, v33
	v_sub_u32_e32 v26, v164, v40
	v_sub_u32_e32 v27, v165, v40
	v_max3_u32 v24, v24, v26, v27
	v_sub_u32_e32 v28, v166, v40
	v_sub_u32_e32 v29, v167, v40
	v_max3_u32 v24, v24, v28, v29
	v_sub_u32_e32 v30, v168, v40
	v_sub_u32_e32 v31, v169, v40
	v_max3_u32 v24, v24, v30, v31
	v_sub_u32_e32 v32, v171, v40
	v_sub_u32_e32 v33, v172, v40
	v_max3_u32 v24, v24, v32, v33
	v_sub_u32_e32 v26, v173, v40
	v_sub_u32_e32 v27, v180, v40
	v_max3_u32 v24, v24, v26, v27
	v_sub_u32_e32 v28, v181, v40
	v_sub_u32_e32 v29, v182, v40
	v_max3_u32 v24, v24, v28, v29
	v_sub_u32_e32 v30, v0, v40
	v_sub_u32_e32 v31, v1, v40
	v_max3_u32 v24, v24, v30, v31
	v_sub_u32_e32 v32, v2, v40
	v_sub_u32_e32 v33, v3, v40
	v_max3_u32 v24, v24, v32, v33
	v_mov_b32_e32 v25, v24
	s_nop 1
	v_permlane16_swap_b32 v24, v25
	s_nop 1
	v_max_u32_e32 v24, v24, v25
	v_mov_b32_e32 v25, v24
	s_nop 1
	v_permlane32_swap_b32 v24, v25
	s_nop 1
	v_max_u32_e32 v24, v24, v25
	v_add_u32_e32 v41, v24, v40
	v_sub_u32_e32 v26, v147, v41
	v_sub_u32_e32 v27, v148, v41
	v_max_u32_e32 v24, v26, v27
	v_sub_u32_e32 v28, v149, v41
	v_sub_u32_e32 v29, v150, v41
	v_max3_u32 v24, v24, v28, v29
	v_sub_u32_e32 v30, v151, v41
	v_sub_u32_e32 v31, v152, v41
	v_max3_u32 v24, v24, v30, v31
	v_sub_u32_e32 v32, v153, v41
	v_sub_u32_e32 v33, v154, v41
	v_max3_u32 v24, v24, v32, v33
	v_sub_u32_e32 v26, v155, v41
	v_sub_u32_e32 v27, v156, v41
	v_max3_u32 v24, v24, v26, v27
	v_sub_u32_e32 v28, v157, v41
	v_sub_u32_e32 v29, v158, v41
	v_max3_u32 v24, v24, v28, v29
	v_sub_u32_e32 v30, v159, v41
	v_sub_u32_e32 v31, v160, v41
	v_max3_u32 v24, v24, v30, v31
	v_sub_u32_e32 v32, v161, v41
	v_sub_u32_e32 v33, v162, v41
	v_max3_u32 v24, v24, v32, v33
	v_sub_u32_e32 v26, v164, v41
	v_sub_u32_e32 v27, v165, v41
	v_max3_u32 v24, v24, v26, v27
	v_sub_u32_e32 v28, v166, v41
	v_sub_u32_e32 v29, v167, v41
	v_max3_u32 v24, v24, v28, v29
	v_sub_u32_e32 v30, v168, v41
	v_sub_u32_e32 v31, v169, v41
	v_max3_u32 v24, v24, v30, v31
	v_sub_u32_e32 v32, v171, v41
	v_sub_u32_e32 v33, v172, v41
	v_max3_u32 v24, v24, v32, v33
	v_sub_u32_e32 v26, v173, v41
	v_sub_u32_e32 v27, v180, v41
	v_max3_u32 v24, v24, v26, v27
	v_sub_u32_e32 v28, v181, v41
	v_sub_u32_e32 v29, v182, v41
; DI void peer_topk_wave(const Params& p, int item, unsigned* lds  ) {
;     ...
;     for (int rr = 0; rr < 16; ++rr) {
;       unsigned m = 0;
; #pragma unroll
;       for (int i = 0; i < 32; ++i) m = umax(m, kk[i]);
;       m = umax(m, (unsigned)__shfl_xor((int)m, 16));
;       m = umax(m, (unsigned)__shfl_xor((int)m, 32));
;       win[pp][rr] = m;
; #pragma unroll
;       for (int i = 0; i < 32; ++i) kk[i] = (kk[i] == m) ? 0u : kk[i];
;     }
	v_max3_u32 v24, v24, v28, v29
	v_sub_u32_e32 v30, v0, v41
	v_sub_u32_e32 v31, v1, v41
	v_max3_u32 v24, v24, v30, v31
	v_sub_u32_e32 v32, v2, v41
	v_sub_u32_e32 v33, v3, v41
	v_max3_u32 v24, v24, v32, v33
	v_mov_b32_e32 v25, v24
	s_nop 1
	v_permlane16_swap_b32 v24, v25
	s_nop 1
	v_max_u32_e32 v24, v24, v25
	v_mov_b32_e32 v25, v24
	s_nop 1
	v_permlane32_swap_b32 v24, v25
	s_nop 1
	v_max_u32_e32 v24, v24, v25
	v_add_u32_e32 v42, v24, v41
	v_sub_u32_e32 v26, v147, v42
	v_sub_u32_e32 v27, v148, v42
	v_max_u32_e32 v24, v26, v27
	v_sub_u32_e32 v28, v149, v42
	v_sub_u32_e32 v29, v150, v42
	v_max3_u32 v24, v24, v28, v29
	v_sub_u32_e32 v30, v151, v42
	v_sub_u32_e32 v31, v152, v42
	v_max3_u32 v24, v24, v30, v31
	v_sub_u32_e32 v32, v153, v42
	v_sub_u32_e32 v33, v154, v42
	v_max3_u32 v24, v24, v32, v33
	v_sub_u32_e32 v26, v155, v42
	v_sub_u32_e32 v27, v156, v42
	v_max3_u32 v24, v24, v26, v27
	v_sub_u32_e32 v28, v157, v42
	v_sub_u32_e32 v29, v158, v42
	v_max3_u32 v24, v24, v28, v29
	v_sub_u32_e32 v30, v159, v42
	v_sub_u32_e32 v31, v160, v42
	v_max3_u32 v24, v24, v30, v31
	v_sub_u32_e32 v32, v161, v42
	v_sub_u32_e32 v33, v162, v42
	v_max3_u32 v24, v24, v32, v33
	v_sub_u32_e32 v26, v164, v42
	v_sub_u32_e32 v27, v165, v42
	v_max3_u32 v24, v24, v26, v27
	v_sub_u32_e32 v28, v166, v42
	v_sub_u32_e32 v29, v167, v42
	v_max3_u32 v24, v24, v28, v29
	v_sub_u32_e32 v30, v168, v42
	v_sub_u32_e32 v31, v169, v42
	v_max3_u32 v24, v24, v30, v31
	v_sub_u32_e32 v32, v171, v42
	v_sub_u32_e32 v33, v172, v42
	v_max3_u32 v24, v24, v32, v33
	v_sub_u32_e32 v26, v173, v42
	v_sub_u32_e32 v27, v180, v42
	v_max3_u32 v24, v24, v26, v27
	v_sub_u32_e32 v28, v181, v42
	v_sub_u32_e32 v29, v182, v42
	v_max3_u32 v24, v24, v28, v29
	v_sub_u32_e32 v30, v0, v42
	v_sub_u32_e32 v31, v1, v42
	v_max3_u32 v24, v24, v30, v31
	v_sub_u32_e32 v32, v2, v42
	v_sub_u32_e32 v33, v3, v42
	v_max3_u32 v24, v24, v32, v33
	v_mov_b32_e32 v25, v24
	s_nop 1
	v_permlane16_swap_b32 v24, v25
	s_nop 1
	v_max_u32_e32 v24, v24, v25
	v_mov_b32_e32 v25, v24
	s_nop 1
	v_permlane32_swap_b32 v24, v25
	s_nop 1
	v_max_u32_e32 v24, v24, v25
	v_add_u32_e32 v43, v24, v42
	v_sub_u32_e32 v26, v147, v43
	v_sub_u32_e32 v27, v148, v43
	v_max_u32_e32 v24, v26, v27
	v_sub_u32_e32 v28, v149, v43
	v_sub_u32_e32 v29, v150, v43
	v_max3_u32 v24, v24, v28, v29
	v_sub_u32_e32 v30, v151, v43
	v_sub_u32_e32 v31, v152, v43
	v_max3_u32 v24, v24, v30, v31
	v_sub_u32_e32 v32, v153, v43
	v_sub_u32_e32 v33, v154, v43
	v_max3_u32 v24, v24, v32, v33
	v_sub_u32_e32 v26, v155, v43
	v_sub_u32_e32 v27, v156, v43
	v_max3_u32 v24, v24, v26, v27
	v_sub_u32_e32 v28, v157, v43
	v_sub_u32_e32 v29, v158, v43
	v_max3_u32 v24, v24, v28, v29
	v_sub_u32_e32 v30, v159, v43
	v_sub_u32_e32 v31, v160, v43
	v_max3_u32 v24, v24, v30, v31
	v_sub_u32_e32 v32, v161, v43
	v_sub_u32_e32 v33, v162, v43
	v_max3_u32 v24, v24, v32, v33
	v_sub_u32_e32 v26, v164, v43
	v_sub_u32_e32 v27, v165, v43
	v_max3_u32 v24, v24, v26, v27
	v_sub_u32_e32 v28, v166, v43
	v_sub_u32_e32 v29, v167, v43
	v_max3_u32 v24, v24, v28, v29
	v_sub_u32_e32 v30, v168, v43
	v_sub_u32_e32 v31, v169, v43
	v_max3_u32 v24, v24, v30, v31
	v_sub_u32_e32 v32, v171, v43
	v_sub_u32_e32 v33, v172, v43
	v_max3_u32 v24, v24, v32, v33
	v_sub_u32_e32 v26, v173, v43
	v_sub_u32_e32 v27, v180, v43
	v_max3_u32 v24, v24, v26, v27
	v_sub_u32_e32 v28, v181, v43
	v_sub_u32_e32 v29, v182, v43
	v_max3_u32 v24, v24, v28, v29
	v_sub_u32_e32 v30, v0, v43
	v_sub_u32_e32 v31, v1, v43
	v_max3_u32 v24, v24, v30, v31
	v_sub_u32_e32 v32, v2, v43
	v_sub_u32_e32 v33, v3, v43
	v_max3_u32 v24, v24, v32, v33
	v_mov_b32_e32 v25, v24
	s_nop 1
	v_permlane16_swap_b32 v24, v25
	s_nop 1
	v_max_u32_e32 v24, v24, v25
	v_mov_b32_e32 v25, v24
	s_nop 1
	v_permlane32_swap_b32 v24, v25
	s_nop 1
	v_max_u32_e32 v24, v24, v25
	v_add_u32_e32 v44, v24, v43
	v_sub_u32_e32 v26, v147, v44
	v_sub_u32_e32 v27, v148, v44
	v_max_u32_e32 v24, v26, v27
	v_sub_u32_e32 v28, v149, v44
	v_sub_u32_e32 v29, v150, v44
	v_max3_u32 v24, v24, v28, v29
	v_sub_u32_e32 v30, v151, v44
	v_sub_u32_e32 v31, v152, v44
	v_max3_u32 v24, v24, v30, v31
	v_sub_u32_e32 v32, v153, v44
	v_sub_u32_e32 v33, v154, v44
	v_max3_u32 v24, v24, v32, v33
	v_sub_u32_e32 v26, v155, v44
	v_sub_u32_e32 v27, v156, v44
	v_max3_u32 v24, v24, v26, v27
	v_sub_u32_e32 v28, v157, v44
	v_sub_u32_e32 v29, v158, v44
	v_max3_u32 v24, v24, v28, v29
	v_sub_u32_e32 v30, v159, v44
	v_sub_u32_e32 v31, v160, v44
	v_max3_u32 v24, v24, v30, v31
	v_sub_u32_e32 v32, v161, v44
	v_sub_u32_e32 v33, v162, v44
	v_max3_u32 v24, v24, v32, v33
	v_sub_u32_e32 v26, v164, v44
	v_sub_u32_e32 v27, v165, v44
	v_max3_u32 v24, v24, v26, v27
	v_sub_u32_e32 v28, v166, v44
	v_sub_u32_e32 v29, v167, v44
	v_max3_u32 v24, v24, v28, v29
	v_sub_u32_e32 v30, v168, v44
	v_sub_u32_e32 v31, v169, v44
	v_max3_u32 v24, v24, v30, v31
	v_sub_u32_e32 v32, v171, v44
	v_sub_u32_e32 v33, v172, v44
	v_max3_u32 v24, v24, v32, v33
	v_sub_u32_e32 v26, v173, v44
	v_sub_u32_e32 v27, v180, v44
	v_max3_u32 v24, v24, v26, v27
	v_sub_u32_e32 v28, v181, v44
	v_sub_u32_e32 v29, v182, v44
	v_max3_u32 v24, v24, v28, v29
	v_sub_u32_e32 v30, v0, v44
	v_sub_u32_e32 v31, v1, v44
	v_max3_u32 v24, v24, v30, v31
	v_sub_u32_e32 v32, v2, v44
	v_sub_u32_e32 v33, v3, v44
	v_max3_u32 v24, v24, v32, v33
	v_mov_b32_e32 v25, v24
	s_nop 1
	v_permlane16_swap_b32 v24, v25
	s_nop 1
	v_max_u32_e32 v24, v24, v25
	v_mov_b32_e32 v25, v24
	s_nop 1
	v_permlane32_swap_b32 v24, v25
	s_nop 1
	v_max_u32_e32 v24, v24, v25
	v_add_u32_e32 v45, v24, v44
	v_sub_u32_e32 v26, v147, v45
	v_sub_u32_e32 v27, v148, v45
	v_max_u32_e32 v24, v26, v27
	v_sub_u32_e32 v28, v149, v45
	v_sub_u32_e32 v29, v150, v45
; DI void peer_topk_wave(const Params& p, int item, unsigned* lds  ) {
;     ...
;     for (int rr = 0; rr < 16; ++rr) {
;       unsigned m = 0;
; #pragma unroll
;       for (int i = 0; i < 32; ++i) m = umax(m, kk[i]);
;       m = umax(m, (unsigned)__shfl_xor((int)m, 16));
;       m = umax(m, (unsigned)__shfl_xor((int)m, 32));
;       win[pp][rr] = m;
; #pragma unroll
;       for (int i = 0; i < 32; ++i) kk[i] = (kk[i] == m) ? 0u : kk[i];
;     }
	v_max3_u32 v24, v24, v28, v29
	v_sub_u32_e32 v30, v151, v45
	v_sub_u32_e32 v31, v152, v45
	v_max3_u32 v24, v24, v30, v31
	v_sub_u32_e32 v32, v153, v45
	v_sub_u32_e32 v33, v154, v45
	v_max3_u32 v24, v24, v32, v33
	v_sub_u32_e32 v26, v155, v45
	v_sub_u32_e32 v27, v156, v45
	v_max3_u32 v24, v24, v26, v27
	v_sub_u32_e32 v28, v157, v45
	v_sub_u32_e32 v29, v158, v45
	v_max3_u32 v24, v24, v28, v29
	v_sub_u32_e32 v30, v159, v45
	v_sub_u32_e32 v31, v160, v45
	v_max3_u32 v24, v24, v30, v31
	v_sub_u32_e32 v32, v161, v45
	v_sub_u32_e32 v33, v162, v45
	v_max3_u32 v24, v24, v32, v33
	v_sub_u32_e32 v26, v164, v45
	v_sub_u32_e32 v27, v165, v45
	v_max3_u32 v24, v24, v26, v27
	v_sub_u32_e32 v28, v166, v45
	v_sub_u32_e32 v29, v167, v45
	v_max3_u32 v24, v24, v28, v29
	v_sub_u32_e32 v30, v168, v45
	v_sub_u32_e32 v31, v169, v45
	v_max3_u32 v24, v24, v30, v31
	v_sub_u32_e32 v32, v171, v45
	v_sub_u32_e32 v33, v172, v45
	v_max3_u32 v24, v24, v32, v33
	v_sub_u32_e32 v26, v173, v45
	v_sub_u32_e32 v27, v180, v45
	v_max3_u32 v24, v24, v26, v27
	v_sub_u32_e32 v28, v181, v45
	v_sub_u32_e32 v29, v182, v45
	v_max3_u32 v24, v24, v28, v29
	v_sub_u32_e32 v30, v0, v45
	v_sub_u32_e32 v31, v1, v45
	v_max3_u32 v24, v24, v30, v31
	v_sub_u32_e32 v32, v2, v45
	v_sub_u32_e32 v33, v3, v45
	v_max3_u32 v24, v24, v32, v33
	v_mov_b32_e32 v25, v24
	s_nop 1
	v_permlane16_swap_b32 v24, v25
	s_nop 1
	v_max_u32_e32 v24, v24, v25
	v_mov_b32_e32 v25, v24
	s_nop 1
	v_permlane32_swap_b32 v24, v25
	s_nop 1
	v_max_u32_e32 v24, v24, v25
	v_add_u32_e32 v46, v24, v45
	v_sub_u32_e32 v26, v147, v46
	v_sub_u32_e32 v27, v148, v46
	v_max_u32_e32 v24, v26, v27
	v_sub_u32_e32 v28, v149, v46
	v_sub_u32_e32 v29, v150, v46
	v_max3_u32 v24, v24, v28, v29
	v_sub_u32_e32 v30, v151, v46
	v_sub_u32_e32 v31, v152, v46
	v_max3_u32 v24, v24, v30, v31
	v_sub_u32_e32 v32, v153, v46
	v_sub_u32_e32 v33, v154, v46
	v_max3_u32 v24, v24, v32, v33
	v_sub_u32_e32 v26, v155, v46
	v_sub_u32_e32 v27, v156, v46
	v_max3_u32 v24, v24, v26, v27
	v_sub_u32_e32 v28, v157, v46
	v_sub_u32_e32 v29, v158, v46
	v_max3_u32 v24, v24, v28, v29
	v_sub_u32_e32 v30, v159, v46
	v_sub_u32_e32 v31, v160, v46
	v_max3_u32 v24, v24, v30, v31
	v_sub_u32_e32 v32, v161, v46
	v_sub_u32_e32 v33, v162, v46
	v_max3_u32 v24, v24, v32, v33
	v_sub_u32_e32 v26, v164, v46
	v_sub_u32_e32 v27, v165, v46
	v_max3_u32 v24, v24, v26, v27
	v_sub_u32_e32 v28, v166, v46
	v_sub_u32_e32 v29, v167, v46
	v_max3_u32 v24, v24, v28, v29
	v_sub_u32_e32 v30, v168, v46
	v_sub_u32_e32 v31, v169, v46
	v_max3_u32 v24, v24, v30, v31
	v_sub_u32_e32 v32, v171, v46
	v_sub_u32_e32 v33, v172, v46
	v_max3_u32 v24, v24, v32, v33
	v_sub_u32_e32 v26, v173, v46
	v_sub_u32_e32 v27, v180, v46
	v_max3_u32 v24, v24, v26, v27
	v_sub_u32_e32 v28, v181, v46
	v_sub_u32_e32 v29, v182, v46
	v_max3_u32 v24, v24, v28, v29
	v_sub_u32_e32 v30, v0, v46
	v_sub_u32_e32 v31, v1, v46
	v_max3_u32 v24, v24, v30, v31
	v_sub_u32_e32 v32, v2, v46
	v_sub_u32_e32 v33, v3, v46
	v_max3_u32 v24, v24, v32, v33
	v_mov_b32_e32 v25, v24
	s_nop 1
	v_permlane16_swap_b32 v24, v25
	s_nop 1
	v_max_u32_e32 v24, v24, v25
	v_mov_b32_e32 v25, v24
	s_nop 1
	v_permlane32_swap_b32 v24, v25
	s_nop 1
	v_max_u32_e32 v24, v24, v25
	v_add_u32_e32 v47, v24, v46
	v_sub_u32_e32 v26, v147, v47
	v_sub_u32_e32 v27, v148, v47
	v_max_u32_e32 v24, v26, v27
	v_sub_u32_e32 v28, v149, v47
	v_sub_u32_e32 v29, v150, v47
	v_max3_u32 v24, v24, v28, v29
	v_sub_u32_e32 v30, v151, v47
	v_sub_u32_e32 v31, v152, v47
	v_max3_u32 v24, v24, v30, v31
	v_sub_u32_e32 v32, v153, v47
	v_sub_u32_e32 v33, v154, v47
	v_max3_u32 v24, v24, v32, v33
	v_sub_u32_e32 v26, v155, v47
	v_sub_u32_e32 v27, v156, v47
	v_max3_u32 v24, v24, v26, v27
	v_sub_u32_e32 v28, v157, v47
	v_sub_u32_e32 v29, v158, v47
	v_max3_u32 v24, v24, v28, v29
	v_sub_u32_e32 v30, v159, v47
	v_sub_u32_e32 v31, v160, v47
	v_max3_u32 v24, v24, v30, v31
	v_sub_u32_e32 v32, v161, v47
	v_sub_u32_e32 v33, v162, v47
	v_max3_u32 v24, v24, v32, v33
	v_sub_u32_e32 v26, v164, v47
	v_sub_u32_e32 v27, v165, v47
	v_max3_u32 v24, v24, v26, v27
	v_sub_u32_e32 v28, v166, v47
	v_sub_u32_e32 v29, v167, v47
	v_max3_u32 v24, v24, v28, v29
	v_sub_u32_e32 v30, v168, v47
	v_sub_u32_e32 v31, v169, v47
	v_max3_u32 v24, v24, v30, v31
	v_sub_u32_e32 v32, v171, v47
	v_sub_u32_e32 v33, v172, v47
	v_max3_u32 v24, v24, v32, v33
	v_sub_u32_e32 v26, v173, v47
	v_sub_u32_e32 v27, v180, v47
	v_max3_u32 v24, v24, v26, v27
	v_sub_u32_e32 v28, v181, v47
	v_sub_u32_e32 v29, v182, v47
	v_max3_u32 v24, v24, v28, v29
	v_sub_u32_e32 v30, v0, v47
	v_sub_u32_e32 v31, v1, v47
	v_max3_u32 v24, v24, v30, v31
	v_sub_u32_e32 v32, v2, v47
	v_sub_u32_e32 v33, v3, v47
	v_max3_u32 v24, v24, v32, v33
	v_mov_b32_e32 v25, v24
	s_nop 1
	v_permlane16_swap_b32 v24, v25
	s_nop 1
	v_max_u32_e32 v24, v24, v25
	v_mov_b32_e32 v25, v24
	s_nop 1
	v_permlane32_swap_b32 v24, v25
	s_nop 1
	v_max_u32_e32 v24, v24, v25
	v_add_u32_e32 v48, v24, v47
	v_sub_u32_e32 v26, v147, v48
	v_sub_u32_e32 v27, v148, v48
	v_max_u32_e32 v24, v26, v27
	v_sub_u32_e32 v28, v149, v48
	v_sub_u32_e32 v29, v150, v48
	v_max3_u32 v24, v24, v28, v29
	v_sub_u32_e32 v30, v151, v48
	v_sub_u32_e32 v31, v152, v48
	v_max3_u32 v24, v24, v30, v31
	v_sub_u32_e32 v32, v153, v48
	v_sub_u32_e32 v33, v154, v48
	v_max3_u32 v24, v24, v32, v33
	v_sub_u32_e32 v26, v155, v48
	v_sub_u32_e32 v27, v156, v48
	v_max3_u32 v24, v24, v26, v27
	v_sub_u32_e32 v28, v157, v48
	v_sub_u32_e32 v29, v158, v48
	v_max3_u32 v24, v24, v28, v29
	v_sub_u32_e32 v30, v159, v48
	v_sub_u32_e32 v31, v160, v48
	v_max3_u32 v24, v24, v30, v31
	v_sub_u32_e32 v32, v161, v48
	v_sub_u32_e32 v33, v162, v48
	v_max3_u32 v24, v24, v32, v33
	v_sub_u32_e32 v26, v164, v48
; DI void peer_topk_wave(const Params& p, int item, unsigned* lds  ) {
;     ...
; #pragma unroll
;     for (int rr = 0; rr < 16; ++rr) {
;       unsigned m = 0;
; #pragma unroll
;       for (int i = 0; i < 32; ++i) m = umax(m, kk[i]);
;       m = umax(m, (unsigned)__shfl_xor((int)m, 16));
;       m = umax(m, (unsigned)__shfl_xor((int)m, 32));
;       win[pp][rr] = m;
; #pragma unroll
;       for (int i = 0; i < 32; ++i) kk[i] = (kk[i] == m) ? 0u : kk[i];
;     }
	v_sub_u32_e32 v27, v165, v48
	v_max3_u32 v24, v24, v26, v27
	v_sub_u32_e32 v28, v166, v48
	v_sub_u32_e32 v29, v167, v48
	v_max3_u32 v24, v24, v28, v29
	v_sub_u32_e32 v30, v168, v48
	v_sub_u32_e32 v31, v169, v48
	v_max3_u32 v24, v24, v30, v31
	v_sub_u32_e32 v32, v171, v48
	v_sub_u32_e32 v33, v172, v48
	v_max3_u32 v24, v24, v32, v33
	v_sub_u32_e32 v26, v173, v48
	v_sub_u32_e32 v27, v180, v48
	v_max3_u32 v24, v24, v26, v27
	v_sub_u32_e32 v28, v181, v48
	v_sub_u32_e32 v29, v182, v48
	v_max3_u32 v24, v24, v28, v29
	v_sub_u32_e32 v30, v0, v48
	v_sub_u32_e32 v31, v1, v48
	v_max3_u32 v24, v24, v30, v31
	v_sub_u32_e32 v32, v2, v48
	v_sub_u32_e32 v33, v3, v48
	v_max3_u32 v24, v24, v32, v33
	v_mov_b32_e32 v25, v24
	s_nop 1
	v_permlane16_swap_b32 v24, v25
	s_nop 1
	v_max_u32_e32 v24, v24, v25
	v_mov_b32_e32 v25, v24
	s_nop 1
	v_permlane32_swap_b32 v24, v25
	s_nop 1
	v_max_u32_e32 v24, v24, v25
	v_add_u32_e32 v49, v24, v48
	v_sub_u32_e32 v26, v147, v49
	v_sub_u32_e32 v27, v148, v49
	v_max_u32_e32 v24, v26, v27
	v_sub_u32_e32 v28, v149, v49
	v_sub_u32_e32 v29, v150, v49
	v_max3_u32 v24, v24, v28, v29
	v_sub_u32_e32 v30, v151, v49
	v_sub_u32_e32 v31, v152, v49
	v_max3_u32 v24, v24, v30, v31
	v_sub_u32_e32 v32, v153, v49
	v_sub_u32_e32 v33, v154, v49
	v_max3_u32 v24, v24, v32, v33
	v_sub_u32_e32 v26, v155, v49
	v_sub_u32_e32 v27, v156, v49
	v_max3_u32 v24, v24, v26, v27
	v_sub_u32_e32 v28, v157, v49
	v_sub_u32_e32 v29, v158, v49
	v_max3_u32 v24, v24, v28, v29
	v_sub_u32_e32 v30, v159, v49
	v_sub_u32_e32 v31, v160, v49
	v_max3_u32 v24, v24, v30, v31
	v_sub_u32_e32 v32, v161, v49
	v_sub_u32_e32 v33, v162, v49
	v_max3_u32 v24, v24, v32, v33
	v_sub_u32_e32 v26, v164, v49
	v_sub_u32_e32 v27, v165, v49
	v_max3_u32 v24, v24, v26, v27
	v_sub_u32_e32 v28, v166, v49
	v_sub_u32_e32 v29, v167, v49
	v_max3_u32 v24, v24, v28, v29
	v_sub_u32_e32 v30, v168, v49
	v_sub_u32_e32 v31, v169, v49
	v_max3_u32 v24, v24, v30, v31
	v_sub_u32_e32 v32, v171, v49
	v_sub_u32_e32 v33, v172, v49
	v_max3_u32 v24, v24, v32, v33
	v_sub_u32_e32 v26, v173, v49
	v_sub_u32_e32 v27, v180, v49
	v_max3_u32 v24, v24, v26, v27
	v_sub_u32_e32 v28, v181, v49
	v_sub_u32_e32 v29, v182, v49
	v_max3_u32 v24, v24, v28, v29
	v_sub_u32_e32 v30, v0, v49
	v_sub_u32_e32 v31, v1, v49
	v_max3_u32 v24, v24, v30, v31
	v_sub_u32_e32 v32, v2, v49
	v_sub_u32_e32 v33, v3, v49
	v_max3_u32 v24, v24, v32, v33
	v_mov_b32_e32 v25, v24
	s_nop 1
	v_permlane16_swap_b32 v24, v25
	s_nop 1
	v_max_u32_e32 v24, v24, v25
	v_mov_b32_e32 v25, v24
	s_nop 1
	v_permlane32_swap_b32 v24, v25
	s_nop 1
	v_max_u32_e32 v24, v24, v25
	v_add_u32_e32 v50, v24, v49
	v_sub_u32_e32 v26, v147, v50
	v_sub_u32_e32 v27, v148, v50
	v_max_u32_e32 v24, v26, v27
	v_sub_u32_e32 v28, v149, v50
	v_sub_u32_e32 v29, v150, v50
	v_max3_u32 v24, v24, v28, v29
	v_sub_u32_e32 v30, v151, v50
	v_sub_u32_e32 v31, v152, v50
	v_max3_u32 v24, v24, v30, v31
	v_sub_u32_e32 v32, v153, v50
	v_sub_u32_e32 v33, v154, v50
	v_max3_u32 v24, v24, v32, v33
	v_sub_u32_e32 v26, v155, v50
	v_sub_u32_e32 v27, v156, v50
	v_max3_u32 v24, v24, v26, v27
	v_sub_u32_e32 v28, v157, v50
	v_sub_u32_e32 v29, v158, v50
	v_max3_u32 v24, v24, v28, v29
	v_sub_u32_e32 v30, v159, v50
	v_sub_u32_e32 v31, v160, v50
	v_max3_u32 v24, v24, v30, v31
	v_sub_u32_e32 v32, v161, v50
	v_sub_u32_e32 v33, v162, v50
	v_max3_u32 v24, v24, v32, v33
	v_sub_u32_e32 v26, v164, v50
	v_sub_u32_e32 v27, v165, v50
	v_max3_u32 v24, v24, v26, v27
	v_sub_u32_e32 v28, v166, v50
	v_sub_u32_e32 v29, v167, v50
	v_max3_u32 v24, v24, v28, v29
	v_sub_u32_e32 v30, v168, v50
	v_sub_u32_e32 v31, v169, v50
	v_max3_u32 v24, v24, v30, v31
	v_sub_u32_e32 v32, v171, v50
	v_sub_u32_e32 v33, v172, v50
	v_max3_u32 v24, v24, v32, v33
	v_sub_u32_e32 v26, v173, v50
	v_sub_u32_e32 v27, v180, v50
	v_max3_u32 v24, v24, v26, v27
	v_sub_u32_e32 v28, v181, v50
	v_sub_u32_e32 v29, v182, v50
	v_max3_u32 v24, v24, v28, v29
	v_sub_u32_e32 v30, v0, v50
	v_sub_u32_e32 v31, v1, v50
	v_max3_u32 v24, v24, v30, v31
	v_sub_u32_e32 v32, v2, v50
	v_sub_u32_e32 v33, v3, v50
	v_max3_u32 v24, v24, v32, v33
	v_mov_b32_e32 v25, v24
	s_nop 1
	v_permlane16_swap_b32 v24, v25
	s_nop 1
	v_max_u32_e32 v24, v24, v25
	v_mov_b32_e32 v25, v24
	s_nop 1
	v_permlane32_swap_b32 v24, v25
	s_nop 1
	v_max_u32_e32 v24, v24, v25
	v_add_u32_e32 v51, v24, v50
	v_sub_u32_e32 v26, v147, v51
	v_sub_u32_e32 v27, v148, v51
	v_max_u32_e32 v24, v26, v27
	v_sub_u32_e32 v28, v149, v51
	v_sub_u32_e32 v29, v150, v51
	v_max3_u32 v24, v24, v28, v29
	v_sub_u32_e32 v30, v151, v51
	v_sub_u32_e32 v31, v152, v51
	v_max3_u32 v24, v24, v30, v31
	v_sub_u32_e32 v32, v153, v51
	v_sub_u32_e32 v33, v154, v51
	v_max3_u32 v24, v24, v32, v33
	v_sub_u32_e32 v26, v155, v51
	v_sub_u32_e32 v27, v156, v51
	v_max3_u32 v24, v24, v26, v27
	v_sub_u32_e32 v28, v157, v51
	v_sub_u32_e32 v29, v158, v51
	v_max3_u32 v24, v24, v28, v29
	v_sub_u32_e32 v30, v159, v51
	v_sub_u32_e32 v31, v160, v51
	v_max3_u32 v24, v24, v30, v31
	v_sub_u32_e32 v32, v161, v51
	v_sub_u32_e32 v33, v162, v51
	v_max3_u32 v24, v24, v32, v33
	v_sub_u32_e32 v26, v164, v51
	v_sub_u32_e32 v27, v165, v51
	v_max3_u32 v24, v24, v26, v27
	v_sub_u32_e32 v28, v166, v51
	v_sub_u32_e32 v29, v167, v51
	v_max3_u32 v24, v24, v28, v29
	v_sub_u32_e32 v30, v168, v51
	v_sub_u32_e32 v31, v169, v51
	v_max3_u32 v24, v24, v30, v31
	v_sub_u32_e32 v32, v171, v51
	v_sub_u32_e32 v33, v172, v51
	v_max3_u32 v24, v24, v32, v33
	v_sub_u32_e32 v26, v173, v51
	v_sub_u32_e32 v27, v180, v51
	v_max3_u32 v24, v24, v26, v27
	v_sub_u32_e32 v28, v181, v51
	v_sub_u32_e32 v29, v182, v51
	v_max3_u32 v24, v24, v28, v29
	v_sub_u32_e32 v30, v0, v51
	v_sub_u32_e32 v31, v1, v51
	v_max3_u32 v24, v24, v30, v31
; DI void peer_topk_wave(const Params& p, int item, unsigned* lds  ) {
;     ...
;     bf16x8 qf[4];
; #pragma unroll
;     for (int ks = 0; ks < 4; ++ks) qf[ks] = *(const bf16x8*)&p.pq[(size_t)(row0 + r) * 2048 + h * 256 + pp * 128 + ks * 32 + kg * 8];
;     ...
; #pragma unroll
;     for (int rr = 0; rr < 16; ++rr) {
;       unsigned m = 0;
; #pragma unroll
;       for (int i = 0; i < 32; ++i) m = umax(m, kk[i]);
;       m = umax(m, (unsigned)__shfl_xor((int)m, 16));
;       m = umax(m, (unsigned)__shfl_xor((int)m, 32));
;       win[pp][rr] = m;
; #pragma unroll
;       for (int i = 0; i < 32; ++i) kk[i] = (kk[i] == m) ? 0u : kk[i];
;     }
	v_sub_u32_e32 v32, v2, v51
	v_sub_u32_e32 v33, v3, v51
	v_max3_u32 v24, v24, v32, v33
	v_mov_b32_e32 v25, v24
	s_nop 1
	v_permlane16_swap_b32 v24, v25
	s_nop 1
	v_max_u32_e32 v24, v24, v25
	v_mov_b32_e32 v25, v24
	s_nop 1
	v_permlane32_swap_b32 v24, v25
	s_nop 1
	v_max_u32_e32 v24, v24, v25
	v_add_u32_e32 v52, v24, v51
	v_sub_u32_e32 v26, v147, v52
	v_sub_u32_e32 v27, v148, v52
	v_max_u32_e32 v24, v26, v27
	v_sub_u32_e32 v28, v149, v52
	v_sub_u32_e32 v29, v150, v52
	v_max3_u32 v24, v24, v28, v29
	v_sub_u32_e32 v30, v151, v52
	v_sub_u32_e32 v31, v152, v52
	v_max3_u32 v24, v24, v30, v31
	v_sub_u32_e32 v32, v153, v52
	v_sub_u32_e32 v33, v154, v52
	v_max3_u32 v24, v24, v32, v33
	v_sub_u32_e32 v26, v155, v52
	v_sub_u32_e32 v27, v156, v52
	v_max3_u32 v24, v24, v26, v27
	v_sub_u32_e32 v28, v157, v52
	v_sub_u32_e32 v29, v158, v52
	v_max3_u32 v24, v24, v28, v29
	v_sub_u32_e32 v30, v159, v52
	v_sub_u32_e32 v31, v160, v52
	v_max3_u32 v24, v24, v30, v31
	v_sub_u32_e32 v32, v161, v52
	v_sub_u32_e32 v33, v162, v52
	v_max3_u32 v24, v24, v32, v33
	v_sub_u32_e32 v26, v164, v52
	v_sub_u32_e32 v27, v165, v52
	v_max3_u32 v24, v24, v26, v27
	v_sub_u32_e32 v28, v166, v52
	v_sub_u32_e32 v29, v167, v52
	v_max3_u32 v24, v24, v28, v29
	v_sub_u32_e32 v30, v168, v52
	v_sub_u32_e32 v31, v169, v52
	v_max3_u32 v24, v24, v30, v31
	v_sub_u32_e32 v32, v171, v52
	v_sub_u32_e32 v33, v172, v52
	v_max3_u32 v24, v24, v32, v33
	v_sub_u32_e32 v26, v173, v52
	v_sub_u32_e32 v27, v180, v52
	v_max3_u32 v24, v24, v26, v27
	v_sub_u32_e32 v28, v181, v52
	v_sub_u32_e32 v29, v182, v52
	v_max3_u32 v24, v24, v28, v29
	v_sub_u32_e32 v30, v0, v52
	v_sub_u32_e32 v31, v1, v52
	v_max3_u32 v24, v24, v30, v31
	v_sub_u32_e32 v32, v2, v52
	v_sub_u32_e32 v33, v3, v52
	v_max3_u32 v24, v24, v32, v33
	v_mov_b32_e32 v25, v24
	s_nop 1
	v_permlane16_swap_b32 v24, v25
	s_nop 1
	v_max_u32_e32 v24, v24, v25
	v_mov_b32_e32 v25, v24
	s_nop 1
	v_permlane32_swap_b32 v24, v25
	s_nop 1
	v_max_u32_e32 v24, v24, v25
	v_add_u32_e32 v53, v24, v52
	v_sub_u32_e32 v26, v147, v53
	v_sub_u32_e32 v27, v148, v53
	v_max_u32_e32 v24, v26, v27
	v_sub_u32_e32 v28, v149, v53
	v_sub_u32_e32 v29, v150, v53
	v_max3_u32 v24, v24, v28, v29
	v_sub_u32_e32 v30, v151, v53
	v_sub_u32_e32 v31, v152, v53
	v_max3_u32 v24, v24, v30, v31
	v_sub_u32_e32 v32, v153, v53
	v_sub_u32_e32 v33, v154, v53
	v_max3_u32 v24, v24, v32, v33
	v_sub_u32_e32 v26, v155, v53
	v_sub_u32_e32 v27, v156, v53
	v_max3_u32 v24, v24, v26, v27
	v_sub_u32_e32 v28, v157, v53
	v_sub_u32_e32 v29, v158, v53
	v_max3_u32 v24, v24, v28, v29
	v_sub_u32_e32 v30, v159, v53
	v_sub_u32_e32 v31, v160, v53
	v_max3_u32 v24, v24, v30, v31
	v_sub_u32_e32 v32, v161, v53
	v_sub_u32_e32 v33, v162, v53
	v_max3_u32 v24, v24, v32, v33
	v_sub_u32_e32 v26, v164, v53
	v_sub_u32_e32 v27, v165, v53
	v_max3_u32 v24, v24, v26, v27
	v_sub_u32_e32 v28, v166, v53
	v_sub_u32_e32 v29, v167, v53
	v_max3_u32 v24, v24, v28, v29
	v_sub_u32_e32 v30, v168, v53
	v_sub_u32_e32 v31, v169, v53
	v_max3_u32 v24, v24, v30, v31
	v_sub_u32_e32 v32, v171, v53
	v_sub_u32_e32 v33, v172, v53
	v_max3_u32 v24, v24, v32, v33
	v_sub_u32_e32 v26, v173, v53
	v_sub_u32_e32 v27, v180, v53
	v_max3_u32 v24, v24, v26, v27
	v_sub_u32_e32 v28, v181, v53
	v_sub_u32_e32 v29, v182, v53
	v_max3_u32 v24, v24, v28, v29
	v_sub_u32_e32 v30, v0, v53
	v_sub_u32_e32 v31, v1, v53
	v_max3_u32 v24, v24, v30, v31
	v_sub_u32_e32 v32, v2, v53
	v_sub_u32_e32 v33, v3, v53
	v_max3_u32 v24, v24, v32, v33
	v_mov_b32_e32 v25, v24
	s_nop 1
	v_permlane16_swap_b32 v24, v25
	s_nop 1
	v_max_u32_e32 v24, v24, v25
	v_mov_b32_e32 v25, v24
	s_nop 1
	v_permlane32_swap_b32 v24, v25
	s_nop 1
	v_max_u32_e32 v24, v24, v25
	v_add_u32_e32 v54, v24, v53
	v_sub_u32_e32 v26, v147, v54
	v_sub_u32_e32 v27, v148, v54
	v_max_u32_e32 v24, v26, v27
	v_sub_u32_e32 v28, v149, v54
	v_sub_u32_e32 v29, v150, v54
	v_max3_u32 v24, v24, v28, v29
	v_sub_u32_e32 v30, v151, v54
	v_sub_u32_e32 v31, v152, v54
	v_max3_u32 v24, v24, v30, v31
	v_sub_u32_e32 v32, v153, v54
	v_sub_u32_e32 v33, v154, v54
	v_max3_u32 v24, v24, v32, v33
	v_sub_u32_e32 v26, v155, v54
	v_sub_u32_e32 v27, v156, v54
	v_max3_u32 v24, v24, v26, v27
	v_sub_u32_e32 v28, v157, v54
	v_sub_u32_e32 v29, v158, v54
	v_max3_u32 v24, v24, v28, v29
	v_sub_u32_e32 v30, v159, v54
	v_sub_u32_e32 v31, v160, v54
	v_max3_u32 v24, v24, v30, v31
	v_sub_u32_e32 v32, v161, v54
	v_sub_u32_e32 v33, v162, v54
	v_max3_u32 v24, v24, v32, v33
	v_sub_u32_e32 v26, v164, v54
	v_sub_u32_e32 v27, v165, v54
	v_max3_u32 v24, v24, v26, v27
	v_sub_u32_e32 v28, v166, v54
	v_sub_u32_e32 v29, v167, v54
	v_max3_u32 v24, v24, v28, v29
	v_sub_u32_e32 v30, v168, v54
	v_sub_u32_e32 v31, v169, v54
	v_max3_u32 v24, v24, v30, v31
	v_sub_u32_e32 v32, v171, v54
	v_sub_u32_e32 v33, v172, v54
	v_max3_u32 v24, v24, v32, v33
	v_sub_u32_e32 v26, v173, v54
	v_sub_u32_e32 v27, v180, v54
	v_max3_u32 v24, v24, v26, v27
	v_sub_u32_e32 v28, v181, v54
	v_sub_u32_e32 v29, v182, v54
	v_max3_u32 v24, v24, v28, v29
	v_sub_u32_e32 v30, v0, v54
	v_sub_u32_e32 v31, v1, v54
	v_max3_u32 v24, v24, v30, v31
	v_sub_u32_e32 v32, v2, v54
	v_sub_u32_e32 v33, v3, v54
	v_max3_u32 v24, v24, v32, v33
	v_mov_b32_e32 v25, v24
	s_nop 1
	v_permlane16_swap_b32 v24, v25
	s_nop 1
	v_max_u32_e32 v24, v24, v25
	v_mov_b32_e32 v25, v24
	s_nop 1
	v_permlane32_swap_b32 v24, v25
	s_nop 1
	v_max_u32_e32 v24, v24, v25
	v_add_u32_e32 v55, v24, v54
	v_mov_b32_e32 v16, v40
	v_mov_b32_e32 v147, v41
	v_mov_b32_e32 v148, v42
	v_mov_b32_e32 v149, v43
	v_mov_b32_e32 v150, v44
	v_mov_b32_e32 v151, v45
	v_mov_b32_e32 v152, v46
	v_mov_b32_e32 v153, v47
	v_mov_b32_e32 v154, v48
	v_mov_b32_e32 v155, v49
	v_mov_b32_e32 v156, v50
	v_mov_b32_e32 v157, v51
	v_mov_b32_e32 v158, v52
	v_mov_b32_e32 v159, v53
	v_mov_b32_e32 v160, v54
	v_mov_b32_e32 v161, v55
	v_lshl_add_u64 v[236:237], v[88:89], 0, s[90:91]
	s_cmp_lg_u32 s88, 0
	s_cbranch_scc1 .Lp10q_mov1
	global_load_dwordx4 v[12:15], v[88:89], off offset:256
	global_load_dwordx4 v[8:11], v[88:89], off offset:320
	global_load_dwordx4 v[4:7], v[88:89], off offset:384
	global_load_dwordx4 v[0:3], v[88:89], off offset:448
	s_branch .Lp10q_done1

; #define MFMA(a, b, c) __builtin_amdgcn_mfma_f32_16x16x32_bf16((a), (b), (c), 0, 0, 0)
; DI unsigned ordf(float f) { unsigned u = __float_as_uint(f); return (u & 0x80000000u) ? ~u : (u | 0x80000000u); }
; DI void peer_topk_wave(const Params& p, int item, unsigned* lds  ) {
;     ...
; #pragma unroll
;     for (int mt = 0; mt < 8; ++mt) {
;       f32x4 a = (f32x4){0.f, 0.f, 0.f, 0.f};
; #pragma unroll
;       for (int ks = 0; ks < 4; ++ks) {
;         bf16x8 kf = *(const bf16x8*)&sk[(mt * 16 + r) * 128 + ks * 32 + kg * 8];
;         a = MFMA(kf, qf[ks], a);
;       }
; #pragma unroll
;       for (int j = 0; j < 4; ++j) kk[mt * 4 + j] = (ordf(a[j]) & ~127u) | (unsigned)(mt * 16 + kg * 4 + j);
;     }
.Lp10q_done1:
	ds_bpermute_b32 v162, v112, v161
	v_readfirstlane_b32 s0, v86
	v_readfirstlane_b32 s1, v87
	s_nop 3
	s_add_u32 s0, s0, 0x8000
	s_addc_u32 s1, s1, 0
	s_add_u32 s2, s0, 0x0
	s_addc_u32 s3, s1, 0
	ds_read_b128 v[24:27], v241 offset:34816
	ds_read_b128 v[28:31], v241 offset:34880
	ds_read_b128 v[32:35], v241 offset:34944
	ds_read_b128 v[36:39], v241 offset:35008
	s_add_u32 s2, s0, 0x1000
	s_addc_u32 s3, s1, 0
	ds_read_b128 v[40:43], v241 offset:39168
	ds_read_b128 v[44:47], v241 offset:39232
	ds_read_b128 v[48:51], v241 offset:39296
	ds_read_b128 v[52:55], v241 offset:39360
	s_add_u32 s2, s0, 0x2000
	s_addc_u32 s3, s1, 0
	ds_read_b128 v[56:59], v241 offset:43520
	ds_read_b128 v[60:63], v241 offset:43584
	ds_read_b128 v[64:67], v241 offset:43648
	ds_read_b128 v[68:71], v241 offset:43712
	s_add_u32 s2, s0, 0x3000
	s_addc_u32 s3, s1, 0
	ds_read_b128 v[72:75], v241 offset:47872
	ds_read_b128 v[76:79], v241 offset:47936
	ds_read_b128 v[80:83], v241 offset:48000
	s_waitcnt vmcnt(0) lgkmcnt(11)
	v_mfma_f32_16x16x32_bf16 v[190:193], v[24:27], v[12:15], 0
	v_mfma_f32_16x16x32_bf16 v[190:193], v[28:31], v[8:11], v[190:193]
	v_mfma_f32_16x16x32_bf16 v[190:193], v[32:35], v[4:7], v[190:193]
	v_mfma_f32_16x16x32_bf16 v[190:193], v[36:39], v[0:3], v[190:193]
	ds_read_b128 v[24:27], v241 offset:48064
	s_add_u32 s2, s0, 0x4000
	s_addc_u32 s3, s1, 0
	ds_read_b128 v[28:31], v241 offset:52224
	ds_read_b128 v[32:35], v241 offset:52288
	ds_read_b128 v[36:39], v241 offset:52352
	s_waitcnt lgkmcnt(11)
	v_mfma_f32_16x16x32_bf16 v[198:201], v[40:43], v[12:15], 0
	v_mfma_f32_16x16x32_bf16 v[198:201], v[44:47], v[8:11], v[198:201]
	v_mfma_f32_16x16x32_bf16 v[198:201], v[48:51], v[4:7], v[198:201]
	v_mfma_f32_16x16x32_bf16 v[198:201], v[52:55], v[0:3], v[198:201]
	ds_read_b128 v[40:43], v241 offset:52416
	s_add_u32 s2, s0, 0x5000
	s_addc_u32 s3, s1, 0
	global_load_dwordx4 v[44:47], v20, s[2:3]
	global_load_dwordx4 v[48:51], v20, s[2:3] offset:64
	global_load_dwordx4 v[52:55], v20, s[2:3] offset:128
	s_nop 7
	s_nop 3
	v_ashrrev_i32_e32 v197, 31, v190
	v_bitop3_b32 v197, v190, v197, s93 bitop3:0x1e
	v_and_or_b32 v88, v197, s80, v170
	v_ashrrev_i32_e32 v202, 31, v191
	v_bitop3_b32 v202, v191, v202, s93 bitop3:0x1e
	v_and_or_b32 v89, v202, s80, v113
	v_ashrrev_i32_e32 v197, 31, v192
	v_bitop3_b32 v197, v192, v197, s93 bitop3:0x1e
	v_and_or_b32 v164, v197, s80, v114
	v_ashrrev_i32_e32 v202, 31, v193
	v_bitop3_b32 v202, v193, v202, s93 bitop3:0x1e
	v_and_or_b32 v165, v202, s80, v115
	s_waitcnt lgkmcnt(8)
	v_mfma_f32_16x16x32_bf16 v[190:193], v[56:59], v[12:15], 0
	v_mfma_f32_16x16x32_bf16 v[190:193], v[60:63], v[8:11], v[190:193]
	v_mfma_f32_16x16x32_bf16 v[190:193], v[64:67], v[4:7], v[190:193]
	v_mfma_f32_16x16x32_bf16 v[190:193], v[68:71], v[0:3], v[190:193]
	global_load_dwordx4 v[56:59], v20, s[2:3] offset:192
	s_add_u32 s2, s0, 0x6000
	s_addc_u32 s3, s1, 0
	global_load_dwordx4 v[60:63], v20, s[2:3]
	global_load_dwordx4 v[64:67], v20, s[2:3] offset:64
	global_load_dwordx4 v[68:71], v20, s[2:3] offset:128
	s_nop 7
	s_nop 3
	v_ashrrev_i32_e32 v197, 31, v198
	v_bitop3_b32 v197, v198, v197, s93 bitop3:0x1e
	v_and_or_b32 v166, v197, s80, v90
	v_ashrrev_i32_e32 v202, 31, v199
	v_bitop3_b32 v202, v199, v202, s93 bitop3:0x1e
	v_and_or_b32 v167, v202, s80, v116
	v_ashrrev_i32_e32 v197, 31, v200
	v_bitop3_b32 v197, v200, v197, s93 bitop3:0x1e
	v_and_or_b32 v168, v197, s80, v117
	v_ashrrev_i32_e32 v202, 31, v201
	v_bitop3_b32 v202, v201, v202, s93 bitop3:0x1e
	v_and_or_b32 v169, v202, s80, v118
	s_waitcnt lgkmcnt(4)
	v_mfma_f32_16x16x32_bf16 v[198:201], v[72:75], v[12:15], 0
	v_mfma_f32_16x16x32_bf16 v[198:201], v[76:79], v[8:11], v[198:201]
	v_mfma_f32_16x16x32_bf16 v[198:201], v[80:83], v[4:7], v[198:201]
	v_mfma_f32_16x16x32_bf16 v[198:201], v[24:27], v[0:3], v[198:201]
	global_load_dwordx4 v[72:75], v20, s[2:3] offset:192
	s_add_u32 s2, s0, 0x7000
	s_addc_u32 s3, s1, 0
	global_load_dwordx4 v[76:79], v20, s[2:3]
	global_load_dwordx4 v[80:83], v20, s[2:3] offset:64
	global_load_dwordx4 v[24:27], v20, s[2:3] offset:128
	s_nop 7
	s_nop 3
	v_ashrrev_i32_e32 v197, 31, v190
	v_bitop3_b32 v197, v190, v197, s93 bitop3:0x1e
	v_and_or_b32 v171, v197, s80, v91
	v_ashrrev_i32_e32 v202, 31, v191
	v_bitop3_b32 v202, v191, v202, s93 bitop3:0x1e
	v_and_or_b32 v172, v202, s80, v119
	v_ashrrev_i32_e32 v197, 31, v192
	v_bitop3_b32 v197, v192, v197, s93 bitop3:0x1e
	v_and_or_b32 v173, v197, s80, v120
	v_ashrrev_i32_e32 v202, 31, v193
	v_bitop3_b32 v202, v193, v202, s93 bitop3:0x1e
	v_and_or_b32 v176, v202, s80, v121
	s_waitcnt lgkmcnt(0)
	v_mfma_f32_16x16x32_bf16 v[190:193], v[28:31], v[12:15], 0
	v_mfma_f32_16x16x32_bf16 v[190:193], v[32:35], v[8:11], v[190:193]
	v_mfma_f32_16x16x32_bf16 v[190:193], v[36:39], v[4:7], v[190:193]
	v_mfma_f32_16x16x32_bf16 v[190:193], v[40:43], v[0:3], v[190:193]
	global_load_dwordx4 v[28:31], v20, s[2:3] offset:192
	s_nop 7
	s_nop 3
	v_ashrrev_i32_e32 v197, 31, v198
	v_bitop3_b32 v197, v198, v197, s93 bitop3:0x1e
	v_and_or_b32 v177, v197, s80, v92
	v_ashrrev_i32_e32 v202, 31, v199
	v_bitop3_b32 v202, v199, v202, s93 bitop3:0x1e
	v_and_or_b32 v178, v202, s80, v122
	v_ashrrev_i32_e32 v197, 31, v200
	v_bitop3_b32 v197, v200, v197, s93 bitop3:0x1e
	v_and_or_b32 v179, v197, s80, v123
	v_ashrrev_i32_e32 v202, 31, v201
	v_bitop3_b32 v202, v201, v202, s93 bitop3:0x1e
	v_and_or_b32 v180, v202, s80, v124
	s_waitcnt vmcnt(8)
; #define MFMA(a, b, c) __builtin_amdgcn_mfma_f32_16x16x32_bf16((a), (b), (c), 0, 0, 0)
; DI unsigned ordf(float f) { unsigned u = __float_as_uint(f); return (u & 0x80000000u) ? ~u : (u | 0x80000000u); }
; DI void peer_topk_wave(const Params& p, int item, unsigned* lds  ) {
;     ...
; #pragma unroll
;     for (int mt = 0; mt < 8; ++mt) {
;       f32x4 a = (f32x4){0.f, 0.f, 0.f, 0.f};
; #pragma unroll
;       for (int ks = 0; ks < 4; ++ks) {
;         bf16x8 kf = *(const bf16x8*)&sk[(mt * 16 + r) * 128 + ks * 32 + kg * 8];
;         a = MFMA(kf, qf[ks], a);
;       }
; #pragma unroll
;       for (int j = 0; j < 4; ++j) kk[mt * 4 + j] = (ordf(a[j]) & ~127u) | (unsigned)(mt * 16 + kg * 4 + j);
;     }
; #pragma unroll
;     for (int rr = 0; rr < 16; ++rr) {
;       unsigned m = 0;
; #pragma unroll
;       for (int i = 0; i < 32; ++i) m = umax(m, kk[i]);
;       m = umax(m, (unsigned)__shfl_xor((int)m, 16));
;       m = umax(m, (unsigned)__shfl_xor((int)m, 32));
;       win[pp][rr] = m;
; #pragma unroll
;       for (int i = 0; i < 32; ++i) kk[i] = (kk[i] == m) ? 0u : kk[i];
;     }
	v_mfma_f32_16x16x32_bf16 v[198:201], v[44:47], v[12:15], 0
	v_mfma_f32_16x16x32_bf16 v[198:201], v[48:51], v[8:11], v[198:201]
	v_mfma_f32_16x16x32_bf16 v[198:201], v[52:55], v[4:7], v[198:201]
	v_mfma_f32_16x16x32_bf16 v[198:201], v[56:59], v[0:3], v[198:201]
	s_nop 7
	s_nop 3
	v_ashrrev_i32_e32 v197, 31, v190
	v_bitop3_b32 v197, v190, v197, s93 bitop3:0x1e
	v_and_or_b32 v181, v197, s80, v93
	v_ashrrev_i32_e32 v202, 31, v191
	v_bitop3_b32 v202, v191, v202, s93 bitop3:0x1e
	v_and_or_b32 v182, v202, s80, v125
	v_ashrrev_i32_e32 v197, 31, v192
	v_bitop3_b32 v197, v192, v197, s93 bitop3:0x1e
	v_and_or_b32 v183, v197, s80, v126
	v_ashrrev_i32_e32 v202, 31, v193
	v_bitop3_b32 v202, v193, v202, s93 bitop3:0x1e
	v_and_or_b32 v184, v202, s80, v127
	s_waitcnt vmcnt(4)
	v_mfma_f32_16x16x32_bf16 v[190:193], v[60:63], v[12:15], 0
	v_mfma_f32_16x16x32_bf16 v[190:193], v[64:67], v[8:11], v[190:193]
	v_mfma_f32_16x16x32_bf16 v[190:193], v[68:71], v[4:7], v[190:193]
	v_mfma_f32_16x16x32_bf16 v[190:193], v[72:75], v[0:3], v[190:193]
	s_nop 7
	s_nop 3
	v_ashrrev_i32_e32 v197, 31, v198
	v_bitop3_b32 v197, v198, v197, s93 bitop3:0x1e
	v_and_or_b32 v185, v197, s80, v94
	v_ashrrev_i32_e32 v202, 31, v199
	v_bitop3_b32 v202, v199, v202, s93 bitop3:0x1e
	v_and_or_b32 v186, v202, s80, v129
	v_ashrrev_i32_e32 v197, 31, v200
	v_bitop3_b32 v197, v200, v197, s93 bitop3:0x1e
	v_and_or_b32 v187, v197, s80, v130
	v_ashrrev_i32_e32 v202, 31, v201
	v_bitop3_b32 v202, v201, v202, s93 bitop3:0x1e
	v_and_or_b32 v188, v202, s80, v131
	s_waitcnt vmcnt(0)
	v_mfma_f32_16x16x32_bf16 v[198:201], v[76:79], v[12:15], 0
	v_mfma_f32_16x16x32_bf16 v[198:201], v[80:83], v[8:11], v[198:201]
	v_mfma_f32_16x16x32_bf16 v[198:201], v[24:27], v[4:7], v[198:201]
	v_mfma_f32_16x16x32_bf16 v[198:201], v[28:31], v[0:3], v[198:201]
	s_nop 7
	s_nop 3
	v_ashrrev_i32_e32 v197, 31, v190
	v_bitop3_b32 v197, v190, v197, s93 bitop3:0x1e
	v_and_or_b32 v189, v197, s80, v95
	v_ashrrev_i32_e32 v202, 31, v191
	v_bitop3_b32 v202, v191, v202, s93 bitop3:0x1e
	v_and_or_b32 v194, v202, s80, v135
	v_ashrrev_i32_e32 v197, 31, v192
	v_bitop3_b32 v197, v192, v197, s93 bitop3:0x1e
	v_and_or_b32 v195, v197, s80, v136
	v_ashrrev_i32_e32 v202, 31, v193
	v_bitop3_b32 v202, v193, v202, s93 bitop3:0x1e
	v_and_or_b32 v196, v202, s80, v137
	s_nop 7
	s_nop 3
	v_ashrrev_i32_e32 v197, 31, v198
	v_bitop3_b32 v197, v198, v197, s93 bitop3:0x1e
	v_and_or_b32 v4, v197, s80, v96
	v_ashrrev_i32_e32 v202, 31, v199
	v_bitop3_b32 v202, v199, v202, s93 bitop3:0x1e
	v_and_or_b32 v1, v202, s80, v138
	v_ashrrev_i32_e32 v197, 31, v200
	v_bitop3_b32 v197, v200, v197, s93 bitop3:0x1e
	v_and_or_b32 v2, v197, s80, v139
	v_ashrrev_i32_e32 v202, 31, v201
	v_bitop3_b32 v202, v201, v202, s93 bitop3:0x1e
	v_and_or_b32 v3, v202, s80, v140
	global_load_dwordx4 v[204:207], v[236:237], off
	global_load_dwordx4 v[208:211], v[236:237], off offset:64
	global_load_dwordx4 v[212:215], v[236:237], off offset:128
	global_load_dwordx4 v[216:219], v[236:237], off offset:192
	global_load_dwordx4 v[220:223], v[236:237], off offset:256
	global_load_dwordx4 v[224:227], v[236:237], off offset:320
	global_load_dwordx4 v[228:231], v[236:237], off offset:384
	global_load_dwordx4 v[232:235], v[236:237], off offset:448
	s_mov_b32 s88, 1
	v_max_u32_e32 v24, v88, v89
	v_max3_u32 v24, v24, v164, v165
	v_max3_u32 v24, v24, v166, v167
	v_max3_u32 v24, v24, v168, v169
	v_max3_u32 v24, v24, v171, v172
	v_max3_u32 v24, v24, v173, v176
	v_max3_u32 v24, v24, v177, v178
	v_max3_u32 v24, v24, v179, v180
	v_max3_u32 v24, v24, v181, v182
	v_max3_u32 v24, v24, v183, v184
	v_max3_u32 v24, v24, v185, v186
	v_max3_u32 v24, v24, v187, v188
	v_max3_u32 v24, v24, v189, v194
	v_max3_u32 v24, v24, v195, v196
	v_max3_u32 v24, v24, v4, v1
	v_max3_u32 v24, v24, v2, v3
	v_mov_b32_e32 v25, v24
	s_nop 1
	v_permlane16_swap_b32 v24, v25
	s_nop 1
	v_max_u32_e32 v24, v24, v25
	v_mov_b32_e32 v25, v24
	s_nop 1
	v_permlane32_swap_b32 v24, v25
	s_nop 1
	v_max_u32_e32 v40, v24, v25
	v_sub_u32_e32 v26, v88, v40
	v_sub_u32_e32 v27, v89, v40
	v_max_u32_e32 v24, v26, v27
	v_sub_u32_e32 v28, v164, v40
	v_sub_u32_e32 v29, v165, v40
	v_max3_u32 v24, v24, v28, v29
	v_sub_u32_e32 v30, v166, v40
	v_sub_u32_e32 v31, v167, v40
	v_max3_u32 v24, v24, v30, v31
	v_sub_u32_e32 v32, v168, v40
	v_sub_u32_e32 v33, v169, v40
	v_max3_u32 v24, v24, v32, v33
	v_sub_u32_e32 v26, v171, v40
	v_sub_u32_e32 v27, v172, v40
	v_max3_u32 v24, v24, v26, v27
	v_sub_u32_e32 v28, v173, v40
	v_sub_u32_e32 v29, v176, v40
	v_max3_u32 v24, v24, v28, v29
	v_sub_u32_e32 v30, v177, v40
	v_sub_u32_e32 v31, v178, v40
	v_max3_u32 v24, v24, v30, v31
	v_sub_u32_e32 v32, v179, v40
	v_sub_u32_e32 v33, v180, v40
	v_max3_u32 v24, v24, v32, v33
	v_sub_u32_e32 v26, v181, v40
	v_sub_u32_e32 v27, v182, v40
	v_max3_u32 v24, v24, v26, v27
	v_sub_u32_e32 v28, v183, v40
	v_sub_u32_e32 v29, v184, v40
	v_max3_u32 v24, v24, v28, v29
	v_sub_u32_e32 v30, v185, v40
	v_sub_u32_e32 v31, v186, v40
	v_max3_u32 v24, v24, v30, v31
	v_sub_u32_e32 v32, v187, v40
	v_sub_u32_e32 v33, v188, v40
	v_max3_u32 v24, v24, v32, v33
	v_sub_u32_e32 v26, v189, v40
	v_sub_u32_e32 v27, v194, v40
	v_max3_u32 v24, v24, v26, v27
	v_sub_u32_e32 v28, v195, v40
	v_sub_u32_e32 v29, v196, v40
	v_max3_u32 v24, v24, v28, v29
	v_sub_u32_e32 v30, v4, v40
	v_sub_u32_e32 v31, v1, v40
	v_max3_u32 v24, v24, v30, v31
	v_sub_u32_e32 v32, v2, v40
	v_sub_u32_e32 v33, v3, v40
	v_max3_u32 v24, v24, v32, v33
	v_mov_b32_e32 v25, v24
	s_nop 1
	v_permlane16_swap_b32 v24, v25
	s_nop 1
	v_max_u32_e32 v24, v24, v25
	v_mov_b32_e32 v25, v24
	s_nop 1
	v_permlane32_swap_b32 v24, v25
	s_nop 1
	v_max_u32_e32 v24, v24, v25
; DI void peer_topk_wave(const Params& p, int item, unsigned* lds  ) {
;     ...
; #pragma unroll
;     for (int rr = 0; rr < 16; ++rr) {
;       unsigned m = 0;
; #pragma unroll
;       for (int i = 0; i < 32; ++i) m = umax(m, kk[i]);
;       m = umax(m, (unsigned)__shfl_xor((int)m, 16));
;       m = umax(m, (unsigned)__shfl_xor((int)m, 32));
;       win[pp][rr] = m;
; #pragma unroll
;       for (int i = 0; i < 32; ++i) kk[i] = (kk[i] == m) ? 0u : kk[i];
;     }
	v_add_u32_e32 v41, v24, v40
	v_sub_u32_e32 v26, v88, v41
	v_sub_u32_e32 v27, v89, v41
	v_max_u32_e32 v24, v26, v27
	v_sub_u32_e32 v28, v164, v41
	v_sub_u32_e32 v29, v165, v41
	v_max3_u32 v24, v24, v28, v29
	v_sub_u32_e32 v30, v166, v41
	v_sub_u32_e32 v31, v167, v41
	v_max3_u32 v24, v24, v30, v31
	v_sub_u32_e32 v32, v168, v41
	v_sub_u32_e32 v33, v169, v41
	v_max3_u32 v24, v24, v32, v33
	v_sub_u32_e32 v26, v171, v41
	v_sub_u32_e32 v27, v172, v41
	v_max3_u32 v24, v24, v26, v27
	v_sub_u32_e32 v28, v173, v41
	v_sub_u32_e32 v29, v176, v41
	v_max3_u32 v24, v24, v28, v29
	v_sub_u32_e32 v30, v177, v41
	v_sub_u32_e32 v31, v178, v41
	v_max3_u32 v24, v24, v30, v31
	v_sub_u32_e32 v32, v179, v41
	v_sub_u32_e32 v33, v180, v41
	v_max3_u32 v24, v24, v32, v33
	v_sub_u32_e32 v26, v181, v41
	v_sub_u32_e32 v27, v182, v41
	v_max3_u32 v24, v24, v26, v27
	v_sub_u32_e32 v28, v183, v41
	v_sub_u32_e32 v29, v184, v41
	v_max3_u32 v24, v24, v28, v29
	v_sub_u32_e32 v30, v185, v41
	v_sub_u32_e32 v31, v186, v41
	v_max3_u32 v24, v24, v30, v31
	v_sub_u32_e32 v32, v187, v41
	v_sub_u32_e32 v33, v188, v41
	v_max3_u32 v24, v24, v32, v33
	v_sub_u32_e32 v26, v189, v41
	v_sub_u32_e32 v27, v194, v41
	v_max3_u32 v24, v24, v26, v27
	v_sub_u32_e32 v28, v195, v41
	v_sub_u32_e32 v29, v196, v41
	v_max3_u32 v24, v24, v28, v29
	v_sub_u32_e32 v30, v4, v41
	v_sub_u32_e32 v31, v1, v41
	v_max3_u32 v24, v24, v30, v31
	v_sub_u32_e32 v32, v2, v41
	v_sub_u32_e32 v33, v3, v41
	v_max3_u32 v24, v24, v32, v33
	v_mov_b32_e32 v25, v24
	s_nop 1
	v_permlane16_swap_b32 v24, v25
	s_nop 1
	v_max_u32_e32 v24, v24, v25
	v_mov_b32_e32 v25, v24
	s_nop 1
	v_permlane32_swap_b32 v24, v25
	s_nop 1
	v_max_u32_e32 v24, v24, v25
	v_add_u32_e32 v42, v24, v41
	v_sub_u32_e32 v26, v88, v42
	v_sub_u32_e32 v27, v89, v42
	v_max_u32_e32 v24, v26, v27
	v_sub_u32_e32 v28, v164, v42
	v_sub_u32_e32 v29, v165, v42
	v_max3_u32 v24, v24, v28, v29
	v_sub_u32_e32 v30, v166, v42
	v_sub_u32_e32 v31, v167, v42
	v_max3_u32 v24, v24, v30, v31
	v_sub_u32_e32 v32, v168, v42
	v_sub_u32_e32 v33, v169, v42
	v_max3_u32 v24, v24, v32, v33
	v_sub_u32_e32 v26, v171, v42
	v_sub_u32_e32 v27, v172, v42
	v_max3_u32 v24, v24, v26, v27
	v_sub_u32_e32 v28, v173, v42
	v_sub_u32_e32 v29, v176, v42
	v_max3_u32 v24, v24, v28, v29
	v_sub_u32_e32 v30, v177, v42
	v_sub_u32_e32 v31, v178, v42
	v_max3_u32 v24, v24, v30, v31
	v_sub_u32_e32 v32, v179, v42
	v_sub_u32_e32 v33, v180, v42
	v_max3_u32 v24, v24, v32, v33
	v_sub_u32_e32 v26, v181, v42
	v_sub_u32_e32 v27, v182, v42
	v_max3_u32 v24, v24, v26, v27
	v_sub_u32_e32 v28, v183, v42
	v_sub_u32_e32 v29, v184, v42
	v_max3_u32 v24, v24, v28, v29
	v_sub_u32_e32 v30, v185, v42
	v_sub_u32_e32 v31, v186, v42
	v_max3_u32 v24, v24, v30, v31
	v_sub_u32_e32 v32, v187, v42
	v_sub_u32_e32 v33, v188, v42
	v_max3_u32 v24, v24, v32, v33
	v_sub_u32_e32 v26, v189, v42
	v_sub_u32_e32 v27, v194, v42
	v_max3_u32 v24, v24, v26, v27
	v_sub_u32_e32 v28, v195, v42
	v_sub_u32_e32 v29, v196, v42
	v_max3_u32 v24, v24, v28, v29
	v_sub_u32_e32 v30, v4, v42
	v_sub_u32_e32 v31, v1, v42
	v_max3_u32 v24, v24, v30, v31
	v_sub_u32_e32 v32, v2, v42
	v_sub_u32_e32 v33, v3, v42
	v_max3_u32 v24, v24, v32, v33
	v_mov_b32_e32 v25, v24
	s_nop 1
	v_permlane16_swap_b32 v24, v25
	s_nop 1
	v_max_u32_e32 v24, v24, v25
	v_mov_b32_e32 v25, v24
	s_nop 1
	v_permlane32_swap_b32 v24, v25
	s_nop 1
	v_max_u32_e32 v24, v24, v25
	v_add_u32_e32 v43, v24, v42
	v_sub_u32_e32 v26, v88, v43
	v_sub_u32_e32 v27, v89, v43
	v_max_u32_e32 v24, v26, v27
	v_sub_u32_e32 v28, v164, v43
	v_sub_u32_e32 v29, v165, v43
	v_max3_u32 v24, v24, v28, v29
	v_sub_u32_e32 v30, v166, v43
	v_sub_u32_e32 v31, v167, v43
	v_max3_u32 v24, v24, v30, v31
	v_sub_u32_e32 v32, v168, v43
	v_sub_u32_e32 v33, v169, v43
	v_max3_u32 v24, v24, v32, v33
	v_sub_u32_e32 v26, v171, v43
	v_sub_u32_e32 v27, v172, v43
	v_max3_u32 v24, v24, v26, v27
	v_sub_u32_e32 v28, v173, v43
	v_sub_u32_e32 v29, v176, v43
	v_max3_u32 v24, v24, v28, v29
	v_sub_u32_e32 v30, v177, v43
	v_sub_u32_e32 v31, v178, v43
	v_max3_u32 v24, v24, v30, v31
	v_sub_u32_e32 v32, v179, v43
	v_sub_u32_e32 v33, v180, v43
	v_max3_u32 v24, v24, v32, v33
	v_sub_u32_e32 v26, v181, v43
	v_sub_u32_e32 v27, v182, v43
	v_max3_u32 v24, v24, v26, v27
	v_sub_u32_e32 v28, v183, v43
	v_sub_u32_e32 v29, v184, v43
	v_max3_u32 v24, v24, v28, v29
	v_sub_u32_e32 v30, v185, v43
	v_sub_u32_e32 v31, v186, v43
	v_max3_u32 v24, v24, v30, v31
	v_sub_u32_e32 v32, v187, v43
	v_sub_u32_e32 v33, v188, v43
	v_max3_u32 v24, v24, v32, v33
	v_sub_u32_e32 v26, v189, v43
	v_sub_u32_e32 v27, v194, v43
	v_max3_u32 v24, v24, v26, v27
	v_sub_u32_e32 v28, v195, v43
	v_sub_u32_e32 v29, v196, v43
	v_max3_u32 v24, v24, v28, v29
	v_sub_u32_e32 v30, v4, v43
	v_sub_u32_e32 v31, v1, v43
	v_max3_u32 v24, v24, v30, v31
	v_sub_u32_e32 v32, v2, v43
	v_sub_u32_e32 v33, v3, v43
	v_max3_u32 v24, v24, v32, v33
	v_mov_b32_e32 v25, v24
	s_nop 1
	v_permlane16_swap_b32 v24, v25
	s_nop 1
	v_max_u32_e32 v24, v24, v25
	v_mov_b32_e32 v25, v24
	s_nop 1
	v_permlane32_swap_b32 v24, v25
	s_nop 1
	v_max_u32_e32 v24, v24, v25
	v_add_u32_e32 v44, v24, v43
	v_sub_u32_e32 v26, v88, v44
	v_sub_u32_e32 v27, v89, v44
	v_max_u32_e32 v24, v26, v27
	v_sub_u32_e32 v28, v164, v44
	v_sub_u32_e32 v29, v165, v44
	v_max3_u32 v24, v24, v28, v29
	v_sub_u32_e32 v30, v166, v44
	v_sub_u32_e32 v31, v167, v44
	v_max3_u32 v24, v24, v30, v31
	v_sub_u32_e32 v32, v168, v44
	v_sub_u32_e32 v33, v169, v44
	v_max3_u32 v24, v24, v32, v33
	v_sub_u32_e32 v26, v171, v44
	v_sub_u32_e32 v27, v172, v44
	v_max3_u32 v24, v24, v26, v27
	v_sub_u32_e32 v28, v173, v44
	v_sub_u32_e32 v29, v176, v44
	v_max3_u32 v24, v24, v28, v29
	v_sub_u32_e32 v30, v177, v44
; DI void peer_topk_wave(const Params& p, int item, unsigned* lds  ) {
;     ...
; #pragma unroll
;     for (int rr = 0; rr < 16; ++rr) {
;       unsigned m = 0;
; #pragma unroll
;       for (int i = 0; i < 32; ++i) m = umax(m, kk[i]);
;       m = umax(m, (unsigned)__shfl_xor((int)m, 16));
;       m = umax(m, (unsigned)__shfl_xor((int)m, 32));
;       win[pp][rr] = m;
; #pragma unroll
;       for (int i = 0; i < 32; ++i) kk[i] = (kk[i] == m) ? 0u : kk[i];
;     }
	v_sub_u32_e32 v31, v178, v44
	v_max3_u32 v24, v24, v30, v31
	v_sub_u32_e32 v32, v179, v44
	v_sub_u32_e32 v33, v180, v44
	v_max3_u32 v24, v24, v32, v33
	v_sub_u32_e32 v26, v181, v44
	v_sub_u32_e32 v27, v182, v44
	v_max3_u32 v24, v24, v26, v27
	v_sub_u32_e32 v28, v183, v44
	v_sub_u32_e32 v29, v184, v44
	v_max3_u32 v24, v24, v28, v29
	v_sub_u32_e32 v30, v185, v44
	v_sub_u32_e32 v31, v186, v44
	v_max3_u32 v24, v24, v30, v31
	v_sub_u32_e32 v32, v187, v44
	v_sub_u32_e32 v33, v188, v44
	v_max3_u32 v24, v24, v32, v33
	v_sub_u32_e32 v26, v189, v44
	v_sub_u32_e32 v27, v194, v44
	v_max3_u32 v24, v24, v26, v27
	v_sub_u32_e32 v28, v195, v44
	v_sub_u32_e32 v29, v196, v44
	v_max3_u32 v24, v24, v28, v29
	v_sub_u32_e32 v30, v4, v44
	v_sub_u32_e32 v31, v1, v44
	v_max3_u32 v24, v24, v30, v31
	v_sub_u32_e32 v32, v2, v44
	v_sub_u32_e32 v33, v3, v44
	v_max3_u32 v24, v24, v32, v33
	v_mov_b32_e32 v25, v24
	s_nop 1
	v_permlane16_swap_b32 v24, v25
	s_nop 1
	v_max_u32_e32 v24, v24, v25
	v_mov_b32_e32 v25, v24
	s_nop 1
	v_permlane32_swap_b32 v24, v25
	s_nop 1
	v_max_u32_e32 v24, v24, v25
	v_add_u32_e32 v45, v24, v44
	v_sub_u32_e32 v26, v88, v45
	v_sub_u32_e32 v27, v89, v45
	v_max_u32_e32 v24, v26, v27
	v_sub_u32_e32 v28, v164, v45
	v_sub_u32_e32 v29, v165, v45
	v_max3_u32 v24, v24, v28, v29
	v_sub_u32_e32 v30, v166, v45
	v_sub_u32_e32 v31, v167, v45
	v_max3_u32 v24, v24, v30, v31
	v_sub_u32_e32 v32, v168, v45
	v_sub_u32_e32 v33, v169, v45
	v_max3_u32 v24, v24, v32, v33
	v_sub_u32_e32 v26, v171, v45
	v_sub_u32_e32 v27, v172, v45
	v_max3_u32 v24, v24, v26, v27
	v_sub_u32_e32 v28, v173, v45
	v_sub_u32_e32 v29, v176, v45
	v_max3_u32 v24, v24, v28, v29
	v_sub_u32_e32 v30, v177, v45
	v_sub_u32_e32 v31, v178, v45
	v_max3_u32 v24, v24, v30, v31
	v_sub_u32_e32 v32, v179, v45
	v_sub_u32_e32 v33, v180, v45
	v_max3_u32 v24, v24, v32, v33
	v_sub_u32_e32 v26, v181, v45
	v_sub_u32_e32 v27, v182, v45
	v_max3_u32 v24, v24, v26, v27
	v_sub_u32_e32 v28, v183, v45
	v_sub_u32_e32 v29, v184, v45
	v_max3_u32 v24, v24, v28, v29
	v_sub_u32_e32 v30, v185, v45
	v_sub_u32_e32 v31, v186, v45
	v_max3_u32 v24, v24, v30, v31
	v_sub_u32_e32 v32, v187, v45
	v_sub_u32_e32 v33, v188, v45
	v_max3_u32 v24, v24, v32, v33
	v_sub_u32_e32 v26, v189, v45
	v_sub_u32_e32 v27, v194, v45
	v_max3_u32 v24, v24, v26, v27
	v_sub_u32_e32 v28, v195, v45
	v_sub_u32_e32 v29, v196, v45
	v_max3_u32 v24, v24, v28, v29
	v_sub_u32_e32 v30, v4, v45
	v_sub_u32_e32 v31, v1, v45
	v_max3_u32 v24, v24, v30, v31
	v_sub_u32_e32 v32, v2, v45
	v_sub_u32_e32 v33, v3, v45
	v_max3_u32 v24, v24, v32, v33
	v_mov_b32_e32 v25, v24
	s_nop 1
	v_permlane16_swap_b32 v24, v25
	s_nop 1
	v_max_u32_e32 v24, v24, v25
	v_mov_b32_e32 v25, v24
	s_nop 1
	v_permlane32_swap_b32 v24, v25
	s_nop 1
	v_max_u32_e32 v24, v24, v25
	v_add_u32_e32 v46, v24, v45
	v_sub_u32_e32 v26, v88, v46
	v_sub_u32_e32 v27, v89, v46
	v_max_u32_e32 v24, v26, v27
	v_sub_u32_e32 v28, v164, v46
	v_sub_u32_e32 v29, v165, v46
	v_max3_u32 v24, v24, v28, v29
	v_sub_u32_e32 v30, v166, v46
	v_sub_u32_e32 v31, v167, v46
	v_max3_u32 v24, v24, v30, v31
	v_sub_u32_e32 v32, v168, v46
	v_sub_u32_e32 v33, v169, v46
	v_max3_u32 v24, v24, v32, v33
	v_sub_u32_e32 v26, v171, v46
	v_sub_u32_e32 v27, v172, v46
	v_max3_u32 v24, v24, v26, v27
	v_sub_u32_e32 v28, v173, v46
	v_sub_u32_e32 v29, v176, v46
	v_max3_u32 v24, v24, v28, v29
	v_sub_u32_e32 v30, v177, v46
	v_sub_u32_e32 v31, v178, v46
	v_max3_u32 v24, v24, v30, v31
	v_sub_u32_e32 v32, v179, v46
	v_sub_u32_e32 v33, v180, v46
	v_max3_u32 v24, v24, v32, v33
	v_sub_u32_e32 v26, v181, v46
	v_sub_u32_e32 v27, v182, v46
	v_max3_u32 v24, v24, v26, v27
	v_sub_u32_e32 v28, v183, v46
	v_sub_u32_e32 v29, v184, v46
	v_max3_u32 v24, v24, v28, v29
	v_sub_u32_e32 v30, v185, v46
	v_sub_u32_e32 v31, v186, v46
	v_max3_u32 v24, v24, v30, v31
	v_sub_u32_e32 v32, v187, v46
	v_sub_u32_e32 v33, v188, v46
	v_max3_u32 v24, v24, v32, v33
	v_sub_u32_e32 v26, v189, v46
	v_sub_u32_e32 v27, v194, v46
	v_max3_u32 v24, v24, v26, v27
	v_sub_u32_e32 v28, v195, v46
	v_sub_u32_e32 v29, v196, v46
	v_max3_u32 v24, v24, v28, v29
	v_sub_u32_e32 v30, v4, v46
	v_sub_u32_e32 v31, v1, v46
	v_max3_u32 v24, v24, v30, v31
	v_sub_u32_e32 v32, v2, v46
	v_sub_u32_e32 v33, v3, v46
	v_max3_u32 v24, v24, v32, v33
	v_mov_b32_e32 v25, v24
	s_nop 1
	v_permlane16_swap_b32 v24, v25
	s_nop 1
	v_max_u32_e32 v24, v24, v25
	v_mov_b32_e32 v25, v24
	s_nop 1
	v_permlane32_swap_b32 v24, v25
	s_nop 1
	v_max_u32_e32 v24, v24, v25
	v_add_u32_e32 v47, v24, v46
	v_sub_u32_e32 v26, v88, v47
	v_sub_u32_e32 v27, v89, v47
	v_max_u32_e32 v24, v26, v27
	v_sub_u32_e32 v28, v164, v47
	v_sub_u32_e32 v29, v165, v47
	v_max3_u32 v24, v24, v28, v29
	v_sub_u32_e32 v30, v166, v47
	v_sub_u32_e32 v31, v167, v47
	v_max3_u32 v24, v24, v30, v31
	v_sub_u32_e32 v32, v168, v47
	v_sub_u32_e32 v33, v169, v47
	v_max3_u32 v24, v24, v32, v33
	v_sub_u32_e32 v26, v171, v47
	v_sub_u32_e32 v27, v172, v47
	v_max3_u32 v24, v24, v26, v27
	v_sub_u32_e32 v28, v173, v47
	v_sub_u32_e32 v29, v176, v47
	v_max3_u32 v24, v24, v28, v29
	v_sub_u32_e32 v30, v177, v47
	v_sub_u32_e32 v31, v178, v47
	v_max3_u32 v24, v24, v30, v31
	v_sub_u32_e32 v32, v179, v47
	v_sub_u32_e32 v33, v180, v47
	v_max3_u32 v24, v24, v32, v33
	v_sub_u32_e32 v26, v181, v47
	v_sub_u32_e32 v27, v182, v47
	v_max3_u32 v24, v24, v26, v27
	v_sub_u32_e32 v28, v183, v47
	v_sub_u32_e32 v29, v184, v47
	v_max3_u32 v24, v24, v28, v29
	v_sub_u32_e32 v30, v185, v47
	v_sub_u32_e32 v31, v186, v47
	v_max3_u32 v24, v24, v30, v31
	v_sub_u32_e32 v32, v187, v47
	v_sub_u32_e32 v33, v188, v47
	v_max3_u32 v24, v24, v32, v33
	v_sub_u32_e32 v26, v189, v47
	v_sub_u32_e32 v27, v194, v47
	v_max3_u32 v24, v24, v26, v27
; DI void peer_topk_wave(const Params& p, int item, unsigned* lds  ) {
;     ...
; #pragma unroll
;     for (int rr = 0; rr < 16; ++rr) {
;       unsigned m = 0;
; #pragma unroll
;       for (int i = 0; i < 32; ++i) m = umax(m, kk[i]);
;       m = umax(m, (unsigned)__shfl_xor((int)m, 16));
;       m = umax(m, (unsigned)__shfl_xor((int)m, 32));
;       win[pp][rr] = m;
; #pragma unroll
;       for (int i = 0; i < 32; ++i) kk[i] = (kk[i] == m) ? 0u : kk[i];
;     }
	v_sub_u32_e32 v28, v195, v47
	v_sub_u32_e32 v29, v196, v47
	v_max3_u32 v24, v24, v28, v29
	v_sub_u32_e32 v30, v4, v47
	v_sub_u32_e32 v31, v1, v47
	v_max3_u32 v24, v24, v30, v31
	v_sub_u32_e32 v32, v2, v47
	v_sub_u32_e32 v33, v3, v47
	v_max3_u32 v24, v24, v32, v33
	v_mov_b32_e32 v25, v24
	s_nop 1
	v_permlane16_swap_b32 v24, v25
	s_nop 1
	v_max_u32_e32 v24, v24, v25
	v_mov_b32_e32 v25, v24
	s_nop 1
	v_permlane32_swap_b32 v24, v25
	s_nop 1
	v_max_u32_e32 v24, v24, v25
	v_add_u32_e32 v48, v24, v47
	v_sub_u32_e32 v26, v88, v48
	v_sub_u32_e32 v27, v89, v48
	v_max_u32_e32 v24, v26, v27
	v_sub_u32_e32 v28, v164, v48
	v_sub_u32_e32 v29, v165, v48
	v_max3_u32 v24, v24, v28, v29
	v_sub_u32_e32 v30, v166, v48
	v_sub_u32_e32 v31, v167, v48
	v_max3_u32 v24, v24, v30, v31
	v_sub_u32_e32 v32, v168, v48
	v_sub_u32_e32 v33, v169, v48
	v_max3_u32 v24, v24, v32, v33
	v_sub_u32_e32 v26, v171, v48
	v_sub_u32_e32 v27, v172, v48
	v_max3_u32 v24, v24, v26, v27
	v_sub_u32_e32 v28, v173, v48
	v_sub_u32_e32 v29, v176, v48
	v_max3_u32 v24, v24, v28, v29
	v_sub_u32_e32 v30, v177, v48
	v_sub_u32_e32 v31, v178, v48
	v_max3_u32 v24, v24, v30, v31
	v_sub_u32_e32 v32, v179, v48
	v_sub_u32_e32 v33, v180, v48
	v_max3_u32 v24, v24, v32, v33
	v_sub_u32_e32 v26, v181, v48
	v_sub_u32_e32 v27, v182, v48
	v_max3_u32 v24, v24, v26, v27
	v_sub_u32_e32 v28, v183, v48
	v_sub_u32_e32 v29, v184, v48
	v_max3_u32 v24, v24, v28, v29
	v_sub_u32_e32 v30, v185, v48
	v_sub_u32_e32 v31, v186, v48
	v_max3_u32 v24, v24, v30, v31
	v_sub_u32_e32 v32, v187, v48
	v_sub_u32_e32 v33, v188, v48
	v_max3_u32 v24, v24, v32, v33
	v_sub_u32_e32 v26, v189, v48
	v_sub_u32_e32 v27, v194, v48
	v_max3_u32 v24, v24, v26, v27
	v_sub_u32_e32 v28, v195, v48
	v_sub_u32_e32 v29, v196, v48
	v_max3_u32 v24, v24, v28, v29
	v_sub_u32_e32 v30, v4, v48
	v_sub_u32_e32 v31, v1, v48
	v_max3_u32 v24, v24, v30, v31
	v_sub_u32_e32 v32, v2, v48
	v_sub_u32_e32 v33, v3, v48
	v_max3_u32 v24, v24, v32, v33
	v_mov_b32_e32 v25, v24
	s_nop 1
	v_permlane16_swap_b32 v24, v25
	s_nop 1
	v_max_u32_e32 v24, v24, v25
	v_mov_b32_e32 v25, v24
	s_nop 1
	v_permlane32_swap_b32 v24, v25
	s_nop 1
	v_max_u32_e32 v24, v24, v25
	v_add_u32_e32 v49, v24, v48
	v_sub_u32_e32 v26, v88, v49
	v_sub_u32_e32 v27, v89, v49
	v_max_u32_e32 v24, v26, v27
	v_sub_u32_e32 v28, v164, v49
	v_sub_u32_e32 v29, v165, v49
	v_max3_u32 v24, v24, v28, v29
	v_sub_u32_e32 v30, v166, v49
	v_sub_u32_e32 v31, v167, v49
	v_max3_u32 v24, v24, v30, v31
	v_sub_u32_e32 v32, v168, v49
	v_sub_u32_e32 v33, v169, v49
	v_max3_u32 v24, v24, v32, v33
	v_sub_u32_e32 v26, v171, v49
	v_sub_u32_e32 v27, v172, v49
	v_max3_u32 v24, v24, v26, v27
	v_sub_u32_e32 v28, v173, v49
	v_sub_u32_e32 v29, v176, v49
	v_max3_u32 v24, v24, v28, v29
	v_sub_u32_e32 v30, v177, v49
	v_sub_u32_e32 v31, v178, v49
	v_max3_u32 v24, v24, v30, v31
	v_sub_u32_e32 v32, v179, v49
	v_sub_u32_e32 v33, v180, v49
	v_max3_u32 v24, v24, v32, v33
	v_sub_u32_e32 v26, v181, v49
	v_sub_u32_e32 v27, v182, v49
	v_max3_u32 v24, v24, v26, v27
	v_sub_u32_e32 v28, v183, v49
	v_sub_u32_e32 v29, v184, v49
	v_max3_u32 v24, v24, v28, v29
	v_sub_u32_e32 v30, v185, v49
	v_sub_u32_e32 v31, v186, v49
	v_max3_u32 v24, v24, v30, v31
	v_sub_u32_e32 v32, v187, v49
	v_sub_u32_e32 v33, v188, v49
	v_max3_u32 v24, v24, v32, v33
	v_sub_u32_e32 v26, v189, v49
	v_sub_u32_e32 v27, v194, v49
	v_max3_u32 v24, v24, v26, v27
	v_sub_u32_e32 v28, v195, v49
	v_sub_u32_e32 v29, v196, v49
	v_max3_u32 v24, v24, v28, v29
	v_sub_u32_e32 v30, v4, v49
	v_sub_u32_e32 v31, v1, v49
	v_max3_u32 v24, v24, v30, v31
	v_sub_u32_e32 v32, v2, v49
	v_sub_u32_e32 v33, v3, v49
	v_max3_u32 v24, v24, v32, v33
	v_mov_b32_e32 v25, v24
	s_nop 1
	v_permlane16_swap_b32 v24, v25
	s_nop 1
	v_max_u32_e32 v24, v24, v25
	v_mov_b32_e32 v25, v24
	s_nop 1
	v_permlane32_swap_b32 v24, v25
	s_nop 1
	v_max_u32_e32 v24, v24, v25
	v_add_u32_e32 v50, v24, v49
	v_sub_u32_e32 v26, v88, v50
	v_sub_u32_e32 v27, v89, v50
	v_max_u32_e32 v24, v26, v27
	v_sub_u32_e32 v28, v164, v50
	v_sub_u32_e32 v29, v165, v50
	v_max3_u32 v24, v24, v28, v29
	v_sub_u32_e32 v30, v166, v50
	v_sub_u32_e32 v31, v167, v50
	v_max3_u32 v24, v24, v30, v31
	v_sub_u32_e32 v32, v168, v50
	v_sub_u32_e32 v33, v169, v50
	v_max3_u32 v24, v24, v32, v33
	v_sub_u32_e32 v26, v171, v50
	v_sub_u32_e32 v27, v172, v50
	v_max3_u32 v24, v24, v26, v27
	v_sub_u32_e32 v28, v173, v50
	v_sub_u32_e32 v29, v176, v50
	v_max3_u32 v24, v24, v28, v29
	v_sub_u32_e32 v30, v177, v50
	v_sub_u32_e32 v31, v178, v50
	v_max3_u32 v24, v24, v30, v31
	v_sub_u32_e32 v32, v179, v50
	v_sub_u32_e32 v33, v180, v50
	v_max3_u32 v24, v24, v32, v33
	v_sub_u32_e32 v26, v181, v50
	v_sub_u32_e32 v27, v182, v50
	v_max3_u32 v24, v24, v26, v27
	v_sub_u32_e32 v28, v183, v50
	v_sub_u32_e32 v29, v184, v50
	v_max3_u32 v24, v24, v28, v29
	v_sub_u32_e32 v30, v185, v50
	v_sub_u32_e32 v31, v186, v50
	v_max3_u32 v24, v24, v30, v31
	v_sub_u32_e32 v32, v187, v50
	v_sub_u32_e32 v33, v188, v50
	v_max3_u32 v24, v24, v32, v33
	v_sub_u32_e32 v26, v189, v50
	v_sub_u32_e32 v27, v194, v50
	v_max3_u32 v24, v24, v26, v27
	v_sub_u32_e32 v28, v195, v50
	v_sub_u32_e32 v29, v196, v50
	v_max3_u32 v24, v24, v28, v29
	v_sub_u32_e32 v30, v4, v50
	v_sub_u32_e32 v31, v1, v50
	v_max3_u32 v24, v24, v30, v31
	v_sub_u32_e32 v32, v2, v50
	v_sub_u32_e32 v33, v3, v50
	v_max3_u32 v24, v24, v32, v33
	v_mov_b32_e32 v25, v24
	s_nop 1
	v_permlane16_swap_b32 v24, v25
	s_nop 1
	v_max_u32_e32 v24, v24, v25
	v_mov_b32_e32 v25, v24
	s_nop 1
	v_permlane32_swap_b32 v24, v25
	s_nop 1
	v_max_u32_e32 v24, v24, v25
	v_add_u32_e32 v51, v24, v50
	v_sub_u32_e32 v26, v88, v51
	v_sub_u32_e32 v27, v89, v51
	v_max_u32_e32 v24, v26, v27
	v_sub_u32_e32 v28, v164, v51
; DI void peer_topk_wave(const Params& p, int item, unsigned* lds  ) {
;     ...
; #pragma unroll
;     for (int rr = 0; rr < 16; ++rr) {
;       unsigned m = 0;
; #pragma unroll
;       for (int i = 0; i < 32; ++i) m = umax(m, kk[i]);
;       m = umax(m, (unsigned)__shfl_xor((int)m, 16));
;       m = umax(m, (unsigned)__shfl_xor((int)m, 32));
;       win[pp][rr] = m;
; #pragma unroll
;       for (int i = 0; i < 32; ++i) kk[i] = (kk[i] == m) ? 0u : kk[i];
;     }
	v_sub_u32_e32 v29, v165, v51
	v_max3_u32 v24, v24, v28, v29
	v_sub_u32_e32 v30, v166, v51
	v_sub_u32_e32 v31, v167, v51
	v_max3_u32 v24, v24, v30, v31
	v_sub_u32_e32 v32, v168, v51
	v_sub_u32_e32 v33, v169, v51
	v_max3_u32 v24, v24, v32, v33
	v_sub_u32_e32 v26, v171, v51
	v_sub_u32_e32 v27, v172, v51
	v_max3_u32 v24, v24, v26, v27
	v_sub_u32_e32 v28, v173, v51
	v_sub_u32_e32 v29, v176, v51
	v_max3_u32 v24, v24, v28, v29
	v_sub_u32_e32 v30, v177, v51
	v_sub_u32_e32 v31, v178, v51
	v_max3_u32 v24, v24, v30, v31
	v_sub_u32_e32 v32, v179, v51
	v_sub_u32_e32 v33, v180, v51
	v_max3_u32 v24, v24, v32, v33
	v_sub_u32_e32 v26, v181, v51
	v_sub_u32_e32 v27, v182, v51
	v_max3_u32 v24, v24, v26, v27
	v_sub_u32_e32 v28, v183, v51
	v_sub_u32_e32 v29, v184, v51
	v_max3_u32 v24, v24, v28, v29
	v_sub_u32_e32 v30, v185, v51
	v_sub_u32_e32 v31, v186, v51
	v_max3_u32 v24, v24, v30, v31
	v_sub_u32_e32 v32, v187, v51
	v_sub_u32_e32 v33, v188, v51
	v_max3_u32 v24, v24, v32, v33
	v_sub_u32_e32 v26, v189, v51
	v_sub_u32_e32 v27, v194, v51
	v_max3_u32 v24, v24, v26, v27
	v_sub_u32_e32 v28, v195, v51
	v_sub_u32_e32 v29, v196, v51
	v_max3_u32 v24, v24, v28, v29
	v_sub_u32_e32 v30, v4, v51
	v_sub_u32_e32 v31, v1, v51
	v_max3_u32 v24, v24, v30, v31
	v_sub_u32_e32 v32, v2, v51
	v_sub_u32_e32 v33, v3, v51
	v_max3_u32 v24, v24, v32, v33
	v_mov_b32_e32 v25, v24
	s_nop 1
	v_permlane16_swap_b32 v24, v25
	s_nop 1
	v_max_u32_e32 v24, v24, v25
	v_mov_b32_e32 v25, v24
	s_nop 1
	v_permlane32_swap_b32 v24, v25
	s_nop 1
	v_max_u32_e32 v24, v24, v25
	v_add_u32_e32 v52, v24, v51
	v_sub_u32_e32 v26, v88, v52
	v_sub_u32_e32 v27, v89, v52
	v_max_u32_e32 v24, v26, v27
	v_sub_u32_e32 v28, v164, v52
	v_sub_u32_e32 v29, v165, v52
	v_max3_u32 v24, v24, v28, v29
	v_sub_u32_e32 v30, v166, v52
	v_sub_u32_e32 v31, v167, v52
	v_max3_u32 v24, v24, v30, v31
	v_sub_u32_e32 v32, v168, v52
	v_sub_u32_e32 v33, v169, v52
	v_max3_u32 v24, v24, v32, v33
	v_sub_u32_e32 v26, v171, v52
	v_sub_u32_e32 v27, v172, v52
	v_max3_u32 v24, v24, v26, v27
	v_sub_u32_e32 v28, v173, v52
	v_sub_u32_e32 v29, v176, v52
	v_max3_u32 v24, v24, v28, v29
	v_sub_u32_e32 v30, v177, v52
	v_sub_u32_e32 v31, v178, v52
	v_max3_u32 v24, v24, v30, v31
	v_sub_u32_e32 v32, v179, v52
	v_sub_u32_e32 v33, v180, v52
	v_max3_u32 v24, v24, v32, v33
	v_sub_u32_e32 v26, v181, v52
	v_sub_u32_e32 v27, v182, v52
	v_max3_u32 v24, v24, v26, v27
	v_sub_u32_e32 v28, v183, v52
	v_sub_u32_e32 v29, v184, v52
	v_max3_u32 v24, v24, v28, v29
	v_sub_u32_e32 v30, v185, v52
	v_sub_u32_e32 v31, v186, v52
	v_max3_u32 v24, v24, v30, v31
	v_sub_u32_e32 v32, v187, v52
	v_sub_u32_e32 v33, v188, v52
	v_max3_u32 v24, v24, v32, v33
	v_sub_u32_e32 v26, v189, v52
	v_sub_u32_e32 v27, v194, v52
	v_max3_u32 v24, v24, v26, v27
	v_sub_u32_e32 v28, v195, v52
	v_sub_u32_e32 v29, v196, v52
	v_max3_u32 v24, v24, v28, v29
	v_sub_u32_e32 v30, v4, v52
	v_sub_u32_e32 v31, v1, v52
	v_max3_u32 v24, v24, v30, v31
	v_sub_u32_e32 v32, v2, v52
	v_sub_u32_e32 v33, v3, v52
	v_max3_u32 v24, v24, v32, v33
	v_mov_b32_e32 v25, v24
	s_nop 1
	v_permlane16_swap_b32 v24, v25
	s_nop 1
	v_max_u32_e32 v24, v24, v25
	v_mov_b32_e32 v25, v24
	s_nop 1
	v_permlane32_swap_b32 v24, v25
	s_nop 1
	v_max_u32_e32 v24, v24, v25
	v_add_u32_e32 v53, v24, v52
	v_sub_u32_e32 v26, v88, v53
	v_sub_u32_e32 v27, v89, v53
	v_max_u32_e32 v24, v26, v27
	v_sub_u32_e32 v28, v164, v53
	v_sub_u32_e32 v29, v165, v53
	v_max3_u32 v24, v24, v28, v29
	v_sub_u32_e32 v30, v166, v53
	v_sub_u32_e32 v31, v167, v53
	v_max3_u32 v24, v24, v30, v31
	v_sub_u32_e32 v32, v168, v53
	v_sub_u32_e32 v33, v169, v53
	v_max3_u32 v24, v24, v32, v33
	v_sub_u32_e32 v26, v171, v53
	v_sub_u32_e32 v27, v172, v53
	v_max3_u32 v24, v24, v26, v27
	v_sub_u32_e32 v28, v173, v53
	v_sub_u32_e32 v29, v176, v53
	v_max3_u32 v24, v24, v28, v29
	v_sub_u32_e32 v30, v177, v53
	v_sub_u32_e32 v31, v178, v53
	v_max3_u32 v24, v24, v30, v31
	v_sub_u32_e32 v32, v179, v53
	v_sub_u32_e32 v33, v180, v53
; DI float unordf(unsigned k) { unsigned u = (k & 0x80000000u) ? (k & 0x7fffffffu) : ~k; return __uint_as_float(u); }
; DI void peer_topk_wave(const Params& p, int item, unsigned* lds  ) {
;     ...
; #pragma unroll
;     for (int rr = 0; rr < 16; ++rr) {
;       unsigned m = 0;
; #pragma unroll
;       for (int i = 0; i < 32; ++i) m = umax(m, kk[i]);
;       m = umax(m, (unsigned)__shfl_xor((int)m, 16));
;       m = umax(m, (unsigned)__shfl_xor((int)m, 32));
;       win[pp][rr] = m;
; #pragma unroll
;       for (int i = 0; i < 32; ++i) kk[i] = (kk[i] == m) ? 0u : kk[i];
;     }
;     ...
;   float f0[16], f1[16];
; #pragma unroll
;   for (int i = 0; i < 16; ++i) { f0[i] = unordf(win[0][i] & ~127u); f1[i] = unordf(win[1][i] & ~127u); }
	v_max3_u32 v24, v24, v32, v33
	v_sub_u32_e32 v26, v181, v53
	v_sub_u32_e32 v27, v182, v53
	v_max3_u32 v24, v24, v26, v27
	v_sub_u32_e32 v28, v183, v53
	v_sub_u32_e32 v29, v184, v53
	v_max3_u32 v24, v24, v28, v29
	v_sub_u32_e32 v30, v185, v53
	v_sub_u32_e32 v31, v186, v53
	v_max3_u32 v24, v24, v30, v31
	v_sub_u32_e32 v32, v187, v53
	v_sub_u32_e32 v33, v188, v53
	v_max3_u32 v24, v24, v32, v33
	v_sub_u32_e32 v26, v189, v53
	v_sub_u32_e32 v27, v194, v53
	v_max3_u32 v24, v24, v26, v27
	v_sub_u32_e32 v28, v195, v53
	v_sub_u32_e32 v29, v196, v53
	v_max3_u32 v24, v24, v28, v29
	v_sub_u32_e32 v30, v4, v53
	v_sub_u32_e32 v31, v1, v53
	v_max3_u32 v24, v24, v30, v31
	v_sub_u32_e32 v32, v2, v53
	v_sub_u32_e32 v33, v3, v53
	v_max3_u32 v24, v24, v32, v33
	v_mov_b32_e32 v25, v24
	s_nop 1
	v_permlane16_swap_b32 v24, v25
	s_nop 1
	v_max_u32_e32 v24, v24, v25
	v_mov_b32_e32 v25, v24
	s_nop 1
	v_permlane32_swap_b32 v24, v25
	s_nop 1
	v_max_u32_e32 v24, v24, v25
	v_add_u32_e32 v54, v24, v53
	v_sub_u32_e32 v26, v88, v54
	v_sub_u32_e32 v27, v89, v54
	v_max_u32_e32 v24, v26, v27
	v_sub_u32_e32 v28, v164, v54
	v_sub_u32_e32 v29, v165, v54
	v_max3_u32 v24, v24, v28, v29
	v_sub_u32_e32 v30, v166, v54
	v_sub_u32_e32 v31, v167, v54
	v_max3_u32 v24, v24, v30, v31
	v_sub_u32_e32 v32, v168, v54
	v_sub_u32_e32 v33, v169, v54
	v_max3_u32 v24, v24, v32, v33
	v_sub_u32_e32 v26, v171, v54
	v_sub_u32_e32 v27, v172, v54
	v_max3_u32 v24, v24, v26, v27
	v_sub_u32_e32 v28, v173, v54
	v_sub_u32_e32 v29, v176, v54
	v_max3_u32 v24, v24, v28, v29
	v_sub_u32_e32 v30, v177, v54
	v_sub_u32_e32 v31, v178, v54
	v_max3_u32 v24, v24, v30, v31
	v_sub_u32_e32 v32, v179, v54
	v_sub_u32_e32 v33, v180, v54
	v_max3_u32 v24, v24, v32, v33
	v_sub_u32_e32 v26, v181, v54
	v_sub_u32_e32 v27, v182, v54
	v_max3_u32 v24, v24, v26, v27
	v_sub_u32_e32 v28, v183, v54
	v_sub_u32_e32 v29, v184, v54
	v_max3_u32 v24, v24, v28, v29
	v_sub_u32_e32 v30, v185, v54
	v_sub_u32_e32 v31, v186, v54
	v_max3_u32 v24, v24, v30, v31
	v_sub_u32_e32 v32, v187, v54
	v_sub_u32_e32 v33, v188, v54
	v_max3_u32 v24, v24, v32, v33
	v_sub_u32_e32 v26, v189, v54
	v_sub_u32_e32 v27, v194, v54
	v_max3_u32 v24, v24, v26, v27
	v_sub_u32_e32 v28, v195, v54
	v_sub_u32_e32 v29, v196, v54
	v_max3_u32 v24, v24, v28, v29
	v_sub_u32_e32 v30, v4, v54
	v_sub_u32_e32 v31, v1, v54
	v_max3_u32 v24, v24, v30, v31
	v_sub_u32_e32 v32, v2, v54
	v_sub_u32_e32 v33, v3, v54
	v_max3_u32 v24, v24, v32, v33
	v_mov_b32_e32 v25, v24
	s_nop 1
	v_permlane16_swap_b32 v24, v25
	s_nop 1
	v_max_u32_e32 v24, v24, v25
	v_mov_b32_e32 v25, v24
	s_nop 1
	v_permlane32_swap_b32 v24, v25
	s_nop 1
	v_max_u32_e32 v24, v24, v25
	v_add_u32_e32 v55, v24, v54
	v_mov_b32_e32 v0, v40
	v_mov_b32_e32 v1, v41
	v_mov_b32_e32 v2, v42
	v_mov_b32_e32 v3, v43
	v_mov_b32_e32 v4, v44
	v_mov_b32_e32 v5, v45
	v_mov_b32_e32 v6, v46
	v_mov_b32_e32 v7, v47
	v_mov_b32_e32 v8, v48
	v_mov_b32_e32 v9, v49
	v_mov_b32_e32 v10, v50
	v_mov_b32_e32 v11, v51
	v_mov_b32_e32 v12, v52
	v_mov_b32_e32 v13, v53
	v_mov_b32_e32 v14, v54
	v_mov_b32_e32 v15, v55
	v_bitop3_b32 v87, v0, s81, v0 bitop3:0xcf
	ds_bpermute_b32 v86, v111, v15
	v_cmp_gt_i32_e32 vcc, 0, v0
	s_waitcnt lgkmcnt(0)
	v_max_u32_e32 v15, v15, v86
	ds_bpermute_b32 v166, v112, v15
	v_and_b32_e32 v86, 0x7fffff80, v0
	v_cndmask_b32_e32 v89, v87, v86, vcc
	v_and_b32_e32 v86, 0x7fffff80, v1
	v_bitop3_b32 v87, v1, s81, v1 bitop3:0xcf
	v_cmp_gt_i32_e32 vcc, 0, v1
	s_nop 1
	v_cndmask_b32_e32 v164, v87, v86, vcc
	v_cmp_lt_i32_e32 vcc, 0, v175
	v_mov_b32_e32 v86, v89
	s_and_saveexec_b64 s[0:1], vcc
	s_cbranch_execz .LBB0_1097
	v_cmp_ne_u32_e32 vcc, 1, v175
	s_and_saveexec_b64 s[2:3], vcc
	s_xor_b64 s[2:3], exec, s[2:3]
	v_cndmask_b32_e64 v86, v164, v89, s[10:11]
	s_andn2_saveexec_b64 s[2:3], s[2:3]
	v_and_b32_e32 v86, 0x7fffff80, v13
	v_bitop3_b32 v87, v13, s81, v13 bitop3:0xcf
	v_cmp_gt_i32_e32 vcc, 0, v13
	s_nop 1
	v_cndmask_b32_e32 v86, v87, v86, vcc
	s_or_b64 exec, exec, s[2:3]
